# in-proj non-head epilogue: modulo-scheduled sigmoid stream alternating transcendental and plain VALU ops
# baseline (speedup 1.0000x reference)
; DI u32x4 pack8(const float* x) { u32x4 v; v.x = cvt_pk(x[0], x[1]); v.y = cvt_pk(x[2], x[3]); v.z = cvt_pk(x[4], x[5]); v.w = cvt_pk(x[6], x[7]); return v; }
; DI float sigmoidf_(float v) { return __builtin_amdgcn_rcpf(1.0f + __expf(-v)); }
;     DI void operator()(const f32x4 (&acc)[2][2][4][2], const Unit& u, int wr, int wc, int fr, int fq) const {
;     ...
;         float rstd[2][4];
; #pragma unroll
;         for (int ai = 0; ai < 2; ++ai)
; #pragma unroll
;             for (int m = 0; m < 4; ++m) rstd[ai][m] = rsqrtf(ssq[row0 + ai * HALF + m * 16] * (1.0f / DM) + EPS);
;         if (u.pn < NHT) {
;     ...
; #pragma unroll
;         for (int bj = 0; bj < 2; ++bj) {
;             const int colw = u.pn * BM + bj * HALF + wc * 32;
;             const int act = colw < C_SILU ? 0 : (colw < C_GATE ? 1 : 2);
; #pragma unroll
;             for (int ai = 0; ai < 2; ++ai)
; #pragma unroll
;                 for (int m = 0; m < 4; ++m) {
;                     float v[8];
; #pragma unroll
;                     for (int j = 0; j < 4; ++j) { v[j] = acc[ai][bj][m][0][j] * rstd[ai][m]; v[4 + j] = acc[ai][bj][m][1][j] * rstd[ai][m]; }
;                     if (act) {
; #pragma unroll
;                         for (int j = 0; j < 8; ++j) { const float sg = sigmoidf_(v[j]); v[j] = act == 1 ? v[j] * sg : sg; }
;                     }
;                     *(u32x4*)(O + (size_t)(row0 + ai * HALF + m * 16) * LDP + col0 + bj * HALF) = pack8(v);
;                 }
;         }
.LBB0_133:
	s_lshl_b32 s4, s10, 8
	v_lshl_add_u32 v170, s2, 8, v147
	v_or_b32_e32 v130, s4, v197
	s_mov_b64 s[2:3], -1
	v_ashrrev_i32_e32 v171, 31, v170
	v_lshl_add_u64 v[132:133], v[170:171], 2, s[58:59]
	global_load_dword v172, v[132:133], off
	global_load_dword v168, v[132:133], off offset:64
	global_load_dword v166, v[132:133], off offset:128
	global_load_dword v164, v[132:133], off offset:192
	global_load_dword v162, v[132:133], off offset:512
	global_load_dword v160, v[132:133], off offset:576
	global_load_dword v158, v[132:133], off offset:640
	global_load_dword v128, v[132:133], off offset:704
	v_add_u32_e32 v222, 16, v170
	v_add_u32_e32 v211, 32, v170
	v_add_u32_e32 v209, 48, v170
	v_add_u32_e32 v207, 0x80, v170
	v_add_u32_e32 v205, 0x90, v170
	v_add_u32_e32 v203, 0xa0, v170
	v_add_u32_e32 v201, 0xb0, v170
	v_ashrrev_i32_e32 v223, 31, v222
	v_ashrrev_i32_e32 v221, 31, v211
	v_ashrrev_i32_e32 v210, 31, v209
	v_ashrrev_i32_e32 v208, 31, v207
	v_ashrrev_i32_e32 v206, 31, v205
	v_ashrrev_i32_e32 v204, 31, v203
	v_ashrrev_i32_e32 v202, 31, v201
	s_cmp_lt_i32 s10, 19
	s_waitcnt vmcnt(0)
	v_fmamk_f32 v172, v172, 0x3a000000, v218
	v_cmp_gt_f32_e32 vcc, s33, v172
	v_mul_f32_e32 v131, 0x4b800000, v172
	s_nop 0
	v_cndmask_b32_e32 v172, v172, v131, vcc
	v_rsq_f32_e32 v172, v172
	s_nop 0
	v_mul_f32_e32 v131, 0x45800000, v172
	v_cndmask_b32_e32 v172, v172, v131, vcc
	v_fmamk_f32 v168, v168, 0x3a000000, v218
	v_cmp_gt_f32_e32 vcc, s33, v168
	v_mul_f32_e32 v131, 0x4b800000, v168
	s_nop 0
	v_cndmask_b32_e32 v168, v168, v131, vcc
	v_rsq_f32_e32 v168, v168
	s_nop 0
	v_mul_f32_e32 v131, 0x45800000, v168
	v_cndmask_b32_e32 v168, v168, v131, vcc
	v_fmamk_f32 v166, v166, 0x3a000000, v218
	v_cmp_gt_f32_e32 vcc, s33, v166
	v_mul_f32_e32 v131, 0x4b800000, v166
	s_nop 0
	v_cndmask_b32_e32 v166, v166, v131, vcc
	v_rsq_f32_e32 v166, v166
	s_nop 0
	v_mul_f32_e32 v131, 0x45800000, v166
	v_cndmask_b32_e32 v166, v166, v131, vcc
	v_fmamk_f32 v164, v164, 0x3a000000, v218
	v_cmp_gt_f32_e32 vcc, s33, v164
	v_mul_f32_e32 v131, 0x4b800000, v164
	s_nop 0
	v_cndmask_b32_e32 v164, v164, v131, vcc
	v_rsq_f32_e32 v164, v164
	s_nop 0
	v_mul_f32_e32 v131, 0x45800000, v164
	v_cndmask_b32_e32 v164, v164, v131, vcc
	v_fmamk_f32 v162, v162, 0x3a000000, v218
	v_cmp_gt_f32_e32 vcc, s33, v162
	v_mul_f32_e32 v131, 0x4b800000, v162
	s_nop 0
	v_cndmask_b32_e32 v162, v162, v131, vcc
	v_rsq_f32_e32 v162, v162
	s_nop 0
	v_mul_f32_e32 v131, 0x45800000, v162
	v_cndmask_b32_e32 v162, v162, v131, vcc
	v_fmamk_f32 v160, v160, 0x3a000000, v218
	v_cmp_gt_f32_e32 vcc, s33, v160
	v_mul_f32_e32 v131, 0x4b800000, v160
	s_nop 0
	v_cndmask_b32_e32 v160, v160, v131, vcc
	v_rsq_f32_e32 v160, v160
	s_nop 0
	v_mul_f32_e32 v131, 0x45800000, v160
	v_cndmask_b32_e32 v160, v160, v131, vcc
	v_fmamk_f32 v158, v158, 0x3a000000, v218
	v_cmp_gt_f32_e32 vcc, s33, v158
	v_mul_f32_e32 v131, 0x4b800000, v158
	s_nop 0
	v_cndmask_b32_e32 v158, v158, v131, vcc
	v_rsq_f32_e32 v158, v158
	s_nop 0
	v_mul_f32_e32 v131, 0x45800000, v158
	v_cndmask_b32_e32 v158, v158, v131, vcc
	v_fmamk_f32 v128, v128, 0x3a000000, v218
	v_cmp_gt_f32_e32 vcc, s33, v128
	v_mul_f32_e32 v131, 0x4b800000, v128
	s_nop 0
	v_cndmask_b32_e32 v128, v128, v131, vcc
	v_rsq_f32_e32 v128, v128
	s_nop 0
	v_mul_f32_e32 v131, 0x45800000, v128
	v_cndmask_b32_e32 v156, v128, v131, vcc
	s_cbranch_scc1 .LBB0_199
	s_or_b32 s8, s4, s83
	s_mov_b32 s5, 0xbfb8aa3b
	s_mov_b32 s6, 0x8c000
	s_mov_b32 s7, 0
	s_mov_b32 s2, 0x2bc000
	s_mov_b32 s3, 0
	v_mov_b64_e32 v[132:133], s[56:57]
	v_mad_i64_i32 v[132:133], vcc, v170, s68, v[132:133]
	v_mov_b32_e32 v131, 0
	v_lshl_add_u64 v[132:133], v[130:131], 1, v[132:133]
	v_mov_b64_e32 v[134:135], v[132:133]
	s_cmpk_lt_i32 s8, 0x1da0
	s_cbranch_scc1 .Lp2e_b0_act0
	s_cmpk_lt_i32 s8, 0x25a0
	s_cbranch_scc1 .Lp2e_b0_act1
	v_mul_f32_e32 v176, v124, v172
	v_mul_f32_e32 v176, s5, v176
	v_mul_f32_e32 v177, v125, v172
	v_exp_f32_e32 v176, v176
	v_mul_f32_e32 v177, s5, v177
	v_add_f32_e32 v176, 1.0, v176
	v_mul_f32_e32 v178, v126, v172
	v_exp_f32_e32 v177, v177
	v_mul_f32_e32 v178, s5, v178
	v_rcp_f32_e32 v176, v176
	v_add_f32_e32 v177, 1.0, v177
	v_mul_f32_e32 v179, v127, v172
	v_exp_f32_e32 v178, v178
	v_mul_f32_e32 v179, s5, v179
	v_rcp_f32_e32 v177, v177
	v_add_f32_e32 v178, 1.0, v178
	v_mul_f32_e32 v180, v120, v172
	v_exp_f32_e32 v179, v179
	v_mul_f32_e32 v180, s5, v180
	v_rcp_f32_e32 v178, v178
	v_add_f32_e32 v179, 1.0, v179
	v_mul_f32_e32 v181, v121, v172
	v_exp_f32_e32 v180, v180
	v_mul_f32_e32 v181, s5, v181
	v_rcp_f32_e32 v179, v179
	v_add_f32_e32 v180, 1.0, v180
	v_mul_f32_e32 v182, v122, v172
	v_exp_f32_e32 v181, v181
	v_mul_f32_e32 v182, s5, v182
	v_rcp_f32_e32 v180, v180
	v_add_f32_e32 v181, 1.0, v181
	v_mul_f32_e32 v183, v123, v172
	v_exp_f32_e32 v182, v182
	v_mul_f32_e32 v183, s5, v183
	v_rcp_f32_e32 v181, v181
	v_add_f32_e32 v182, 1.0, v182
	v_mul_f32_e32 v202, v108, v168
	v_exp_f32_e32 v183, v183
	v_mul_f32_e32 v202, s5, v202
	v_rcp_f32_e32 v182, v182
	v_add_f32_e32 v183, 1.0, v183
	v_mul_f32_e32 v203, v109, v168
	v_exp_f32_e32 v202, v202
	v_mul_f32_e32 v203, s5, v203
	v_rcp_f32_e32 v183, v183
	v_add_f32_e32 v202, 1.0, v202
	s_nop 0
	v_cvt_pk_bf16_f32 v184, v176, v177
	v_cvt_pk_bf16_f32 v185, v178, v179
	v_cvt_pk_bf16_f32 v186, v180, v181
	v_cvt_pk_bf16_f32 v187, v182, v183
	global_store_dwordx4 v[134:135], v[184:187], off
	v_lshl_add_u64 v[134:135], v[134:135], 0, s[6:7]
	v_mul_f32_e32 v204, v110, v168
	v_exp_f32_e32 v203, v203
	v_mul_f32_e32 v204, s5, v204
	v_rcp_f32_e32 v202, v202
	v_add_f32_e32 v203, 1.0, v203
	v_mul_f32_e32 v205, v111, v168
	v_exp_f32_e32 v204, v204
	v_mul_f32_e32 v205, s5, v205
	v_rcp_f32_e32 v203, v203
; DI u32x4 pack8(const float* x) { u32x4 v; v.x = cvt_pk(x[0], x[1]); v.y = cvt_pk(x[2], x[3]); v.z = cvt_pk(x[4], x[5]); v.w = cvt_pk(x[6], x[7]); return v; }
; DI float sigmoidf_(float v) { return __builtin_amdgcn_rcpf(1.0f + __expf(-v)); }
;     DI void operator()(const f32x4 (&acc)[2][2][4][2], const Unit& u, int wr, int wc, int fr, int fq) const {
;     ...
;         for (int bj = 0; bj < 2; ++bj) {
;             const int colw = u.pn * BM + bj * HALF + wc * 32;
;             const int act = colw < C_SILU ? 0 : (colw < C_GATE ? 1 : 2);
; #pragma unroll
;             for (int ai = 0; ai < 2; ++ai)
; #pragma unroll
;                 for (int m = 0; m < 4; ++m) {
;                     float v[8];
; #pragma unroll
;                     for (int j = 0; j < 4; ++j) { v[j] = acc[ai][bj][m][0][j] * rstd[ai][m]; v[4 + j] = acc[ai][bj][m][1][j] * rstd[ai][m]; }
;                     if (act) {
; #pragma unroll
;                         for (int j = 0; j < 8; ++j) { const float sg = sigmoidf_(v[j]); v[j] = act == 1 ? v[j] * sg : sg; }
;                     }
;                     *(u32x4*)(O + (size_t)(row0 + ai * HALF + m * 16) * LDP + col0 + bj * HALF) = pack8(v);
;                 }
	v_add_f32_e32 v204, 1.0, v204
	v_mul_f32_e32 v206, v104, v168
	v_exp_f32_e32 v205, v205
	v_mul_f32_e32 v206, s5, v206
	v_rcp_f32_e32 v204, v204
	v_add_f32_e32 v205, 1.0, v205
	v_mul_f32_e32 v207, v105, v168
	v_exp_f32_e32 v206, v206
	v_mul_f32_e32 v207, s5, v207
	v_rcp_f32_e32 v205, v205
	v_add_f32_e32 v206, 1.0, v206
	v_mul_f32_e32 v208, v106, v168
	v_exp_f32_e32 v207, v207
	v_mul_f32_e32 v208, s5, v208
	v_rcp_f32_e32 v206, v206
	v_add_f32_e32 v207, 1.0, v207
	v_mul_f32_e32 v209, v107, v168
	v_exp_f32_e32 v208, v208
	v_mul_f32_e32 v209, s5, v209
	v_rcp_f32_e32 v207, v207
	v_add_f32_e32 v208, 1.0, v208
	v_mul_f32_e32 v176, v92, v166
	v_exp_f32_e32 v209, v209
	v_mul_f32_e32 v176, s5, v176
	v_rcp_f32_e32 v208, v208
	v_add_f32_e32 v209, 1.0, v209
	v_mul_f32_e32 v177, v93, v166
	v_exp_f32_e32 v176, v176
	v_mul_f32_e32 v177, s5, v177
	v_rcp_f32_e32 v209, v209
	v_add_f32_e32 v176, 1.0, v176
	s_nop 0
	v_cvt_pk_bf16_f32 v228, v202, v203
	v_cvt_pk_bf16_f32 v229, v204, v205
	v_cvt_pk_bf16_f32 v230, v206, v207
	v_cvt_pk_bf16_f32 v231, v208, v209
	global_store_dwordx4 v[134:135], v[228:231], off
	v_lshl_add_u64 v[134:135], v[134:135], 0, s[6:7]
	v_mul_f32_e32 v178, v94, v166
	v_exp_f32_e32 v177, v177
	v_mul_f32_e32 v178, s5, v178
	v_rcp_f32_e32 v176, v176
	v_add_f32_e32 v177, 1.0, v177
	v_mul_f32_e32 v179, v95, v166
	v_exp_f32_e32 v178, v178
	v_mul_f32_e32 v179, s5, v179
	v_rcp_f32_e32 v177, v177
	v_add_f32_e32 v178, 1.0, v178
	v_mul_f32_e32 v180, v88, v166
	v_exp_f32_e32 v179, v179
	v_mul_f32_e32 v180, s5, v180
	v_rcp_f32_e32 v178, v178
	v_add_f32_e32 v179, 1.0, v179
	v_mul_f32_e32 v181, v89, v166
	v_exp_f32_e32 v180, v180
	v_mul_f32_e32 v181, s5, v181
	v_rcp_f32_e32 v179, v179
	v_add_f32_e32 v180, 1.0, v180
	v_mul_f32_e32 v182, v90, v166
	v_exp_f32_e32 v181, v181
	v_mul_f32_e32 v182, s5, v182
	v_rcp_f32_e32 v180, v180
	v_add_f32_e32 v181, 1.0, v181
	v_mul_f32_e32 v183, v91, v166
	v_exp_f32_e32 v182, v182
	v_mul_f32_e32 v183, s5, v183
	v_rcp_f32_e32 v181, v181
	v_add_f32_e32 v182, 1.0, v182
	v_mul_f32_e32 v202, v76, v164
	v_exp_f32_e32 v183, v183
	v_mul_f32_e32 v202, s5, v202
	v_rcp_f32_e32 v182, v182
	v_add_f32_e32 v183, 1.0, v183
	v_mul_f32_e32 v203, v77, v164
	v_exp_f32_e32 v202, v202
	v_mul_f32_e32 v203, s5, v203
	v_rcp_f32_e32 v183, v183
	v_add_f32_e32 v202, 1.0, v202
	s_nop 0
	v_cvt_pk_bf16_f32 v184, v176, v177
	v_cvt_pk_bf16_f32 v185, v178, v179
	v_cvt_pk_bf16_f32 v186, v180, v181
	v_cvt_pk_bf16_f32 v187, v182, v183
	global_store_dwordx4 v[134:135], v[184:187], off
	v_lshl_add_u64 v[134:135], v[134:135], 0, s[6:7]
	v_mul_f32_e32 v204, v78, v164
	v_exp_f32_e32 v203, v203
	v_mul_f32_e32 v204, s5, v204
	v_rcp_f32_e32 v202, v202
	v_add_f32_e32 v203, 1.0, v203
	v_mul_f32_e32 v205, v79, v164
	v_exp_f32_e32 v204, v204
	v_mul_f32_e32 v205, s5, v205
	v_rcp_f32_e32 v203, v203
	v_add_f32_e32 v204, 1.0, v204
	v_mul_f32_e32 v206, v72, v164
	v_exp_f32_e32 v205, v205
	v_mul_f32_e32 v206, s5, v206
	v_rcp_f32_e32 v204, v204
	v_add_f32_e32 v205, 1.0, v205
	v_mul_f32_e32 v207, v73, v164
	v_exp_f32_e32 v206, v206
	v_mul_f32_e32 v207, s5, v207
	v_rcp_f32_e32 v205, v205
	v_add_f32_e32 v206, 1.0, v206
	v_mul_f32_e32 v208, v74, v164
	v_exp_f32_e32 v207, v207
	v_mul_f32_e32 v208, s5, v208
	v_rcp_f32_e32 v206, v206
	v_add_f32_e32 v207, 1.0, v207
	v_mul_f32_e32 v209, v75, v164
	v_exp_f32_e32 v208, v208
	v_mul_f32_e32 v209, s5, v209
	v_rcp_f32_e32 v207, v207
	v_add_f32_e32 v208, 1.0, v208
	v_mul_f32_e32 v176, v60, v162
	v_exp_f32_e32 v209, v209
	v_mul_f32_e32 v176, s5, v176
	v_rcp_f32_e32 v208, v208
	v_add_f32_e32 v209, 1.0, v209
	v_mul_f32_e32 v177, v61, v162
	v_exp_f32_e32 v176, v176
	v_mul_f32_e32 v177, s5, v177
	v_rcp_f32_e32 v209, v209
	v_add_f32_e32 v176, 1.0, v176
	s_nop 0
	v_cvt_pk_bf16_f32 v228, v202, v203
	v_cvt_pk_bf16_f32 v229, v204, v205
	v_cvt_pk_bf16_f32 v230, v206, v207
	v_cvt_pk_bf16_f32 v231, v208, v209
	global_store_dwordx4 v[134:135], v[228:231], off
	v_lshl_add_u64 v[134:135], v[134:135], 0, s[2:3]
	v_mul_f32_e32 v178, v62, v162
	v_exp_f32_e32 v177, v177
	v_mul_f32_e32 v178, s5, v178
	v_rcp_f32_e32 v176, v176
	v_add_f32_e32 v177, 1.0, v177
	v_mul_f32_e32 v179, v63, v162
	v_exp_f32_e32 v178, v178
	v_mul_f32_e32 v179, s5, v179
	v_rcp_f32_e32 v177, v177
	v_add_f32_e32 v178, 1.0, v178
	v_mul_f32_e32 v180, v56, v162
	v_exp_f32_e32 v179, v179
	v_mul_f32_e32 v180, s5, v180
	v_rcp_f32_e32 v178, v178
	v_add_f32_e32 v179, 1.0, v179
	v_mul_f32_e32 v181, v57, v162
	v_exp_f32_e32 v180, v180
	v_mul_f32_e32 v181, s5, v181
	v_rcp_f32_e32 v179, v179
	v_add_f32_e32 v180, 1.0, v180
	v_mul_f32_e32 v182, v58, v162
	v_exp_f32_e32 v181, v181
	v_mul_f32_e32 v182, s5, v182
	v_rcp_f32_e32 v180, v180
	v_add_f32_e32 v181, 1.0, v181
	v_mul_f32_e32 v183, v59, v162
	v_exp_f32_e32 v182, v182
	v_mul_f32_e32 v183, s5, v183
	v_rcp_f32_e32 v181, v181
	v_add_f32_e32 v182, 1.0, v182
	v_mul_f32_e32 v202, v44, v160
	v_exp_f32_e32 v183, v183
	v_mul_f32_e32 v202, s5, v202
	v_rcp_f32_e32 v182, v182
	v_add_f32_e32 v183, 1.0, v183
	v_mul_f32_e32 v203, v45, v160
	v_exp_f32_e32 v202, v202
	v_mul_f32_e32 v203, s5, v203
	v_rcp_f32_e32 v183, v183
	v_add_f32_e32 v202, 1.0, v202
	s_nop 0
	v_cvt_pk_bf16_f32 v184, v176, v177
	v_cvt_pk_bf16_f32 v185, v178, v179
	v_cvt_pk_bf16_f32 v186, v180, v181
	v_cvt_pk_bf16_f32 v187, v182, v183
	global_store_dwordx4 v[134:135], v[184:187], off
	v_lshl_add_u64 v[134:135], v[134:135], 0, s[6:7]
	v_mul_f32_e32 v204, v46, v160
	v_exp_f32_e32 v203, v203
	v_mul_f32_e32 v204, s5, v204
	v_rcp_f32_e32 v202, v202
	v_add_f32_e32 v203, 1.0, v203
	v_mul_f32_e32 v205, v47, v160
	v_exp_f32_e32 v204, v204
	v_mul_f32_e32 v205, s5, v205
	v_rcp_f32_e32 v203, v203
	v_add_f32_e32 v204, 1.0, v204
; DI u32x4 pack8(const float* x) { u32x4 v; v.x = cvt_pk(x[0], x[1]); v.y = cvt_pk(x[2], x[3]); v.z = cvt_pk(x[4], x[5]); v.w = cvt_pk(x[6], x[7]); return v; }
; DI float sigmoidf_(float v) { return __builtin_amdgcn_rcpf(1.0f + __expf(-v)); }
;     DI void operator()(const f32x4 (&acc)[2][2][4][2], const Unit& u, int wr, int wc, int fr, int fq) const {
;     ...
;         for (int bj = 0; bj < 2; ++bj) {
;             const int colw = u.pn * BM + bj * HALF + wc * 32;
;             const int act = colw < C_SILU ? 0 : (colw < C_GATE ? 1 : 2);
; #pragma unroll
;             for (int ai = 0; ai < 2; ++ai)
; #pragma unroll
;                 for (int m = 0; m < 4; ++m) {
;                     float v[8];
; #pragma unroll
;                     for (int j = 0; j < 4; ++j) { v[j] = acc[ai][bj][m][0][j] * rstd[ai][m]; v[4 + j] = acc[ai][bj][m][1][j] * rstd[ai][m]; }
;                     if (act) {
; #pragma unroll
;                         for (int j = 0; j < 8; ++j) { const float sg = sigmoidf_(v[j]); v[j] = act == 1 ? v[j] * sg : sg; }
;                     }
;                     *(u32x4*)(O + (size_t)(row0 + ai * HALF + m * 16) * LDP + col0 + bj * HALF) = pack8(v);
;                 }
	v_mul_f32_e32 v206, v40, v160
	v_exp_f32_e32 v205, v205
	v_mul_f32_e32 v206, s5, v206
	v_rcp_f32_e32 v204, v204
	v_add_f32_e32 v205, 1.0, v205
	v_mul_f32_e32 v207, v41, v160
	v_exp_f32_e32 v206, v206
	v_mul_f32_e32 v207, s5, v207
	v_rcp_f32_e32 v205, v205
	v_add_f32_e32 v206, 1.0, v206
	v_mul_f32_e32 v208, v42, v160
	v_exp_f32_e32 v207, v207
	v_mul_f32_e32 v208, s5, v208
	v_rcp_f32_e32 v206, v206
	v_add_f32_e32 v207, 1.0, v207
	v_mul_f32_e32 v209, v43, v160
	v_exp_f32_e32 v208, v208
	v_mul_f32_e32 v209, s5, v209
	v_rcp_f32_e32 v207, v207
	v_add_f32_e32 v208, 1.0, v208
	v_mul_f32_e32 v176, v28, v158
	v_exp_f32_e32 v209, v209
	v_mul_f32_e32 v176, s5, v176
	v_rcp_f32_e32 v208, v208
	v_add_f32_e32 v209, 1.0, v209
	v_mul_f32_e32 v177, v29, v158
	v_exp_f32_e32 v176, v176
	v_mul_f32_e32 v177, s5, v177
	v_rcp_f32_e32 v209, v209
	v_add_f32_e32 v176, 1.0, v176
	s_nop 0
	v_cvt_pk_bf16_f32 v228, v202, v203
	v_cvt_pk_bf16_f32 v229, v204, v205
	v_cvt_pk_bf16_f32 v230, v206, v207
	v_cvt_pk_bf16_f32 v231, v208, v209
	global_store_dwordx4 v[134:135], v[228:231], off
	v_lshl_add_u64 v[134:135], v[134:135], 0, s[6:7]
	v_mul_f32_e32 v178, v30, v158
	v_exp_f32_e32 v177, v177
	v_mul_f32_e32 v178, s5, v178
	v_rcp_f32_e32 v176, v176
	v_add_f32_e32 v177, 1.0, v177
	v_mul_f32_e32 v179, v31, v158
	v_exp_f32_e32 v178, v178
	v_mul_f32_e32 v179, s5, v179
	v_rcp_f32_e32 v177, v177
	v_add_f32_e32 v178, 1.0, v178
	v_mul_f32_e32 v180, v24, v158
	v_exp_f32_e32 v179, v179
	v_mul_f32_e32 v180, s5, v180
	v_rcp_f32_e32 v178, v178
	v_add_f32_e32 v179, 1.0, v179
	v_mul_f32_e32 v181, v25, v158
	v_exp_f32_e32 v180, v180
	v_mul_f32_e32 v181, s5, v181
	v_rcp_f32_e32 v179, v179
	v_add_f32_e32 v180, 1.0, v180
	v_mul_f32_e32 v182, v26, v158
	v_exp_f32_e32 v181, v181
	v_mul_f32_e32 v182, s5, v182
	v_rcp_f32_e32 v180, v180
	v_add_f32_e32 v181, 1.0, v181
	v_mul_f32_e32 v183, v27, v158
	v_exp_f32_e32 v182, v182
	v_mul_f32_e32 v183, s5, v183
	v_rcp_f32_e32 v181, v181
	v_add_f32_e32 v182, 1.0, v182
	v_mul_f32_e32 v202, v12, v156
	v_exp_f32_e32 v183, v183
	v_mul_f32_e32 v202, s5, v202
	v_rcp_f32_e32 v182, v182
	v_add_f32_e32 v183, 1.0, v183
	v_mul_f32_e32 v203, v13, v156
	v_exp_f32_e32 v202, v202
	v_mul_f32_e32 v203, s5, v203
	v_rcp_f32_e32 v183, v183
	v_add_f32_e32 v202, 1.0, v202
	s_nop 0
	v_cvt_pk_bf16_f32 v184, v176, v177
	v_cvt_pk_bf16_f32 v185, v178, v179
	v_cvt_pk_bf16_f32 v186, v180, v181
	v_cvt_pk_bf16_f32 v187, v182, v183
	global_store_dwordx4 v[134:135], v[184:187], off
	v_lshl_add_u64 v[134:135], v[134:135], 0, s[6:7]
	v_mul_f32_e32 v204, v14, v156
	v_exp_f32_e32 v203, v203
	v_mul_f32_e32 v204, s5, v204
	v_rcp_f32_e32 v202, v202
	v_add_f32_e32 v203, 1.0, v203
	v_mul_f32_e32 v205, v15, v156
	v_exp_f32_e32 v204, v204
	v_mul_f32_e32 v205, s5, v205
	v_rcp_f32_e32 v203, v203
	v_add_f32_e32 v204, 1.0, v204
	v_mul_f32_e32 v206, v8, v156
	v_exp_f32_e32 v205, v205
	v_mul_f32_e32 v206, s5, v206
	v_rcp_f32_e32 v204, v204
	v_add_f32_e32 v205, 1.0, v205
	v_mul_f32_e32 v207, v9, v156
	v_exp_f32_e32 v206, v206
	v_mul_f32_e32 v207, s5, v207
	v_rcp_f32_e32 v205, v205
	v_add_f32_e32 v206, 1.0, v206
	v_mul_f32_e32 v208, v10, v156
	v_exp_f32_e32 v207, v207
	v_mul_f32_e32 v208, s5, v208
	v_rcp_f32_e32 v206, v206
	v_add_f32_e32 v207, 1.0, v207
	v_mul_f32_e32 v209, v11, v156
	v_exp_f32_e32 v208, v208
	v_mul_f32_e32 v209, s5, v209
	v_rcp_f32_e32 v207, v207
	v_add_f32_e32 v208, 1.0, v208
	v_exp_f32_e32 v209, v209
	v_rcp_f32_e32 v208, v208
	v_add_f32_e32 v209, 1.0, v209
	v_rcp_f32_e32 v209, v209
	s_nop 0
	v_cvt_pk_bf16_f32 v228, v202, v203
	v_cvt_pk_bf16_f32 v229, v204, v205
	v_cvt_pk_bf16_f32 v230, v206, v207
	v_cvt_pk_bf16_f32 v231, v208, v209
	global_store_dwordx4 v[134:135], v[228:231], off
	s_branch .Lp2e_b0_done
.Lp2e_b0_act1:
	v_mul_f32_e32 v188, v124, v172
	v_mul_f32_e32 v176, s5, v188
	v_mul_f32_e32 v189, v125, v172
	v_exp_f32_e32 v176, v176
	v_mul_f32_e32 v177, s5, v189
	v_add_f32_e32 v176, 1.0, v176
	v_mul_f32_e32 v190, v126, v172
	v_exp_f32_e32 v177, v177
	v_mul_f32_e32 v178, s5, v190
	v_rcp_f32_e32 v176, v176
	v_add_f32_e32 v177, 1.0, v177
	v_mul_f32_e32 v191, v127, v172
	v_exp_f32_e32 v178, v178
	v_mul_f32_e32 v179, s5, v191
	v_rcp_f32_e32 v177, v177
	v_add_f32_e32 v178, 1.0, v178
	v_mul_f32_e32 v176, v188, v176
	v_mul_f32_e32 v192, v120, v172
	v_exp_f32_e32 v179, v179
	v_mul_f32_e32 v180, s5, v192
	v_rcp_f32_e32 v178, v178
	v_add_f32_e32 v179, 1.0, v179
	v_mul_f32_e32 v177, v189, v177
	v_mul_f32_e32 v193, v121, v172
	v_exp_f32_e32 v180, v180
	v_mul_f32_e32 v181, s5, v193
	v_rcp_f32_e32 v179, v179
	v_add_f32_e32 v180, 1.0, v180
	v_mul_f32_e32 v178, v190, v178
	v_mul_f32_e32 v194, v122, v172
	v_exp_f32_e32 v181, v181
	v_mul_f32_e32 v182, s5, v194
	v_rcp_f32_e32 v180, v180
	v_add_f32_e32 v181, 1.0, v181
	v_mul_f32_e32 v179, v191, v179
	v_mul_f32_e32 v195, v123, v172
	v_exp_f32_e32 v182, v182
	v_mul_f32_e32 v183, s5, v195
	v_rcp_f32_e32 v181, v181
	v_add_f32_e32 v182, 1.0, v182
	v_mul_f32_e32 v180, v192, v180
	v_mul_f32_e32 v222, v108, v168
	v_exp_f32_e32 v183, v183
	v_mul_f32_e32 v202, s5, v222
	v_rcp_f32_e32 v182, v182
	v_add_f32_e32 v183, 1.0, v183
	v_mul_f32_e32 v181, v193, v181
	v_mul_f32_e32 v223, v109, v168
	v_exp_f32_e32 v202, v202
	v_mul_f32_e32 v203, s5, v223
	v_rcp_f32_e32 v183, v183
	v_add_f32_e32 v202, 1.0, v202
	v_mul_f32_e32 v182, v194, v182
	v_mul_f32_e32 v224, v110, v168
	v_exp_f32_e32 v203, v203
	v_mul_f32_e32 v204, s5, v224
	v_rcp_f32_e32 v202, v202
	v_add_f32_e32 v203, 1.0, v203
	v_mul_f32_e32 v183, v195, v183
	v_cvt_pk_bf16_f32 v184, v176, v177
	v_cvt_pk_bf16_f32 v185, v178, v179
	v_cvt_pk_bf16_f32 v186, v180, v181
	v_cvt_pk_bf16_f32 v187, v182, v183
; DI u32x4 pack8(const float* x) { u32x4 v; v.x = cvt_pk(x[0], x[1]); v.y = cvt_pk(x[2], x[3]); v.z = cvt_pk(x[4], x[5]); v.w = cvt_pk(x[6], x[7]); return v; }
; DI float sigmoidf_(float v) { return __builtin_amdgcn_rcpf(1.0f + __expf(-v)); }
;     DI void operator()(const f32x4 (&acc)[2][2][4][2], const Unit& u, int wr, int wc, int fr, int fq) const {
;     ...
;         for (int bj = 0; bj < 2; ++bj) {
;             const int colw = u.pn * BM + bj * HALF + wc * 32;
;             const int act = colw < C_SILU ? 0 : (colw < C_GATE ? 1 : 2);
; #pragma unroll
;             for (int ai = 0; ai < 2; ++ai)
; #pragma unroll
;                 for (int m = 0; m < 4; ++m) {
;                     float v[8];
; #pragma unroll
;                     for (int j = 0; j < 4; ++j) { v[j] = acc[ai][bj][m][0][j] * rstd[ai][m]; v[4 + j] = acc[ai][bj][m][1][j] * rstd[ai][m]; }
;                     if (act) {
; #pragma unroll
;                         for (int j = 0; j < 8; ++j) { const float sg = sigmoidf_(v[j]); v[j] = act == 1 ? v[j] * sg : sg; }
;                     }
;                     *(u32x4*)(O + (size_t)(row0 + ai * HALF + m * 16) * LDP + col0 + bj * HALF) = pack8(v);
;                 }
	global_store_dwordx4 v[134:135], v[184:187], off
	v_lshl_add_u64 v[134:135], v[134:135], 0, s[6:7]
	v_mul_f32_e32 v225, v111, v168
	v_exp_f32_e32 v204, v204
	v_mul_f32_e32 v205, s5, v225
	v_rcp_f32_e32 v203, v203
	v_add_f32_e32 v204, 1.0, v204
	v_mul_f32_e32 v202, v222, v202
	v_mul_f32_e32 v226, v104, v168
	v_exp_f32_e32 v205, v205
	v_mul_f32_e32 v206, s5, v226
	v_rcp_f32_e32 v204, v204
	v_add_f32_e32 v205, 1.0, v205
	v_mul_f32_e32 v203, v223, v203
	v_mul_f32_e32 v227, v105, v168
	v_exp_f32_e32 v206, v206
	v_mul_f32_e32 v207, s5, v227
	v_rcp_f32_e32 v205, v205
	v_add_f32_e32 v206, 1.0, v206
	v_mul_f32_e32 v204, v224, v204
	v_mul_f32_e32 v232, v106, v168
	v_exp_f32_e32 v207, v207
	v_mul_f32_e32 v208, s5, v232
	v_rcp_f32_e32 v206, v206
	v_add_f32_e32 v207, 1.0, v207
	v_mul_f32_e32 v205, v225, v205
	v_mul_f32_e32 v233, v107, v168
	v_exp_f32_e32 v208, v208
	v_mul_f32_e32 v209, s5, v233
	v_rcp_f32_e32 v207, v207
	v_add_f32_e32 v208, 1.0, v208
	v_mul_f32_e32 v206, v226, v206
	v_mul_f32_e32 v188, v92, v166
	v_exp_f32_e32 v209, v209
	v_mul_f32_e32 v176, s5, v188
	v_rcp_f32_e32 v208, v208
	v_add_f32_e32 v209, 1.0, v209
	v_mul_f32_e32 v207, v227, v207
	v_mul_f32_e32 v189, v93, v166
	v_exp_f32_e32 v176, v176
	v_mul_f32_e32 v177, s5, v189
	v_rcp_f32_e32 v209, v209
	v_add_f32_e32 v176, 1.0, v176
	v_mul_f32_e32 v208, v232, v208
	v_mul_f32_e32 v190, v94, v166
	v_exp_f32_e32 v177, v177
	v_mul_f32_e32 v178, s5, v190
	v_rcp_f32_e32 v176, v176
	v_add_f32_e32 v177, 1.0, v177
	v_mul_f32_e32 v209, v233, v209
	v_cvt_pk_bf16_f32 v228, v202, v203
	v_cvt_pk_bf16_f32 v229, v204, v205
	v_cvt_pk_bf16_f32 v230, v206, v207
	v_cvt_pk_bf16_f32 v231, v208, v209
	global_store_dwordx4 v[134:135], v[228:231], off
	v_lshl_add_u64 v[134:135], v[134:135], 0, s[6:7]
	v_mul_f32_e32 v191, v95, v166
	v_exp_f32_e32 v178, v178
	v_mul_f32_e32 v179, s5, v191
	v_rcp_f32_e32 v177, v177
	v_add_f32_e32 v178, 1.0, v178
	v_mul_f32_e32 v176, v188, v176
	v_mul_f32_e32 v192, v88, v166
	v_exp_f32_e32 v179, v179
	v_mul_f32_e32 v180, s5, v192
	v_rcp_f32_e32 v178, v178
	v_add_f32_e32 v179, 1.0, v179
	v_mul_f32_e32 v177, v189, v177
	v_mul_f32_e32 v193, v89, v166
	v_exp_f32_e32 v180, v180
	v_mul_f32_e32 v181, s5, v193
	v_rcp_f32_e32 v179, v179
	v_add_f32_e32 v180, 1.0, v180
	v_mul_f32_e32 v178, v190, v178
	v_mul_f32_e32 v194, v90, v166
	v_exp_f32_e32 v181, v181
	v_mul_f32_e32 v182, s5, v194
	v_rcp_f32_e32 v180, v180
	v_add_f32_e32 v181, 1.0, v181
	v_mul_f32_e32 v179, v191, v179
	v_mul_f32_e32 v195, v91, v166
	v_exp_f32_e32 v182, v182
	v_mul_f32_e32 v183, s5, v195
	v_rcp_f32_e32 v181, v181
	v_add_f32_e32 v182, 1.0, v182
	v_mul_f32_e32 v180, v192, v180
	v_mul_f32_e32 v222, v76, v164
	v_exp_f32_e32 v183, v183
	v_mul_f32_e32 v202, s5, v222
	v_rcp_f32_e32 v182, v182
	v_add_f32_e32 v183, 1.0, v183
	v_mul_f32_e32 v181, v193, v181
	v_mul_f32_e32 v223, v77, v164
	v_exp_f32_e32 v202, v202
	v_mul_f32_e32 v203, s5, v223
	v_rcp_f32_e32 v183, v183
	v_add_f32_e32 v202, 1.0, v202
	v_mul_f32_e32 v182, v194, v182
	v_mul_f32_e32 v224, v78, v164
	v_exp_f32_e32 v203, v203
	v_mul_f32_e32 v204, s5, v224
	v_rcp_f32_e32 v202, v202
	v_add_f32_e32 v203, 1.0, v203
	v_mul_f32_e32 v183, v195, v183
	v_cvt_pk_bf16_f32 v184, v176, v177
	v_cvt_pk_bf16_f32 v185, v178, v179
	v_cvt_pk_bf16_f32 v186, v180, v181
	v_cvt_pk_bf16_f32 v187, v182, v183
	global_store_dwordx4 v[134:135], v[184:187], off
	v_lshl_add_u64 v[134:135], v[134:135], 0, s[6:7]
	v_mul_f32_e32 v225, v79, v164
	v_exp_f32_e32 v204, v204
	v_mul_f32_e32 v205, s5, v225
	v_rcp_f32_e32 v203, v203
	v_add_f32_e32 v204, 1.0, v204
	v_mul_f32_e32 v202, v222, v202
	v_mul_f32_e32 v226, v72, v164
	v_exp_f32_e32 v205, v205
	v_mul_f32_e32 v206, s5, v226
	v_rcp_f32_e32 v204, v204
	v_add_f32_e32 v205, 1.0, v205
	v_mul_f32_e32 v203, v223, v203
	v_mul_f32_e32 v227, v73, v164
	v_exp_f32_e32 v206, v206
	v_mul_f32_e32 v207, s5, v227
	v_rcp_f32_e32 v205, v205
	v_add_f32_e32 v206, 1.0, v206
	v_mul_f32_e32 v204, v224, v204
	v_mul_f32_e32 v232, v74, v164
	v_exp_f32_e32 v207, v207
	v_mul_f32_e32 v208, s5, v232
	v_rcp_f32_e32 v206, v206
	v_add_f32_e32 v207, 1.0, v207
	v_mul_f32_e32 v205, v225, v205
	v_mul_f32_e32 v233, v75, v164
	v_exp_f32_e32 v208, v208
	v_mul_f32_e32 v209, s5, v233
	v_rcp_f32_e32 v207, v207
	v_add_f32_e32 v208, 1.0, v208
	v_mul_f32_e32 v206, v226, v206
	v_mul_f32_e32 v188, v60, v162
	v_exp_f32_e32 v209, v209
	v_mul_f32_e32 v176, s5, v188
	v_rcp_f32_e32 v208, v208
	v_add_f32_e32 v209, 1.0, v209
	v_mul_f32_e32 v207, v227, v207
	v_mul_f32_e32 v189, v61, v162
	v_exp_f32_e32 v176, v176
	v_mul_f32_e32 v177, s5, v189
	v_rcp_f32_e32 v209, v209
	v_add_f32_e32 v176, 1.0, v176
	v_mul_f32_e32 v208, v232, v208
	v_mul_f32_e32 v190, v62, v162
	v_exp_f32_e32 v177, v177
	v_mul_f32_e32 v178, s5, v190
	v_rcp_f32_e32 v176, v176
	v_add_f32_e32 v177, 1.0, v177
	v_mul_f32_e32 v209, v233, v209
	v_cvt_pk_bf16_f32 v228, v202, v203
	v_cvt_pk_bf16_f32 v229, v204, v205
	v_cvt_pk_bf16_f32 v230, v206, v207
	v_cvt_pk_bf16_f32 v231, v208, v209
	global_store_dwordx4 v[134:135], v[228:231], off
	v_lshl_add_u64 v[134:135], v[134:135], 0, s[2:3]
	v_mul_f32_e32 v191, v63, v162
	v_exp_f32_e32 v178, v178
	v_mul_f32_e32 v179, s5, v191
	v_rcp_f32_e32 v177, v177
	v_add_f32_e32 v178, 1.0, v178
	v_mul_f32_e32 v176, v188, v176
	v_mul_f32_e32 v192, v56, v162
	v_exp_f32_e32 v179, v179
	v_mul_f32_e32 v180, s5, v192
	v_rcp_f32_e32 v178, v178
	v_add_f32_e32 v179, 1.0, v179
	v_mul_f32_e32 v177, v189, v177
	v_mul_f32_e32 v193, v57, v162
	v_exp_f32_e32 v180, v180
	v_mul_f32_e32 v181, s5, v193
	v_rcp_f32_e32 v179, v179
	v_add_f32_e32 v180, 1.0, v180
	v_mul_f32_e32 v178, v190, v178
	v_mul_f32_e32 v194, v58, v162
	v_exp_f32_e32 v181, v181
; DI u32x4 pack8(const float* x) { u32x4 v; v.x = cvt_pk(x[0], x[1]); v.y = cvt_pk(x[2], x[3]); v.z = cvt_pk(x[4], x[5]); v.w = cvt_pk(x[6], x[7]); return v; }
; DI float sigmoidf_(float v) { return __builtin_amdgcn_rcpf(1.0f + __expf(-v)); }
;     DI void operator()(const f32x4 (&acc)[2][2][4][2], const Unit& u, int wr, int wc, int fr, int fq) const {
;     ...
;         for (int bj = 0; bj < 2; ++bj) {
;             const int colw = u.pn * BM + bj * HALF + wc * 32;
;             const int act = colw < C_SILU ? 0 : (colw < C_GATE ? 1 : 2);
; #pragma unroll
;             for (int ai = 0; ai < 2; ++ai)
; #pragma unroll
;                 for (int m = 0; m < 4; ++m) {
;                     float v[8];
; #pragma unroll
;                     for (int j = 0; j < 4; ++j) { v[j] = acc[ai][bj][m][0][j] * rstd[ai][m]; v[4 + j] = acc[ai][bj][m][1][j] * rstd[ai][m]; }
;                     if (act) {
; #pragma unroll
;                         for (int j = 0; j < 8; ++j) { const float sg = sigmoidf_(v[j]); v[j] = act == 1 ? v[j] * sg : sg; }
;                     }
;                     *(u32x4*)(O + (size_t)(row0 + ai * HALF + m * 16) * LDP + col0 + bj * HALF) = pack8(v);
;                 }
	v_mul_f32_e32 v182, s5, v194
	v_rcp_f32_e32 v180, v180
	v_add_f32_e32 v181, 1.0, v181
	v_mul_f32_e32 v179, v191, v179
	v_mul_f32_e32 v195, v59, v162
	v_exp_f32_e32 v182, v182
	v_mul_f32_e32 v183, s5, v195
	v_rcp_f32_e32 v181, v181
	v_add_f32_e32 v182, 1.0, v182
	v_mul_f32_e32 v180, v192, v180
	v_mul_f32_e32 v222, v44, v160
	v_exp_f32_e32 v183, v183
	v_mul_f32_e32 v202, s5, v222
	v_rcp_f32_e32 v182, v182
	v_add_f32_e32 v183, 1.0, v183
	v_mul_f32_e32 v181, v193, v181
	v_mul_f32_e32 v223, v45, v160
	v_exp_f32_e32 v202, v202
	v_mul_f32_e32 v203, s5, v223
	v_rcp_f32_e32 v183, v183
	v_add_f32_e32 v202, 1.0, v202
	v_mul_f32_e32 v182, v194, v182
	v_mul_f32_e32 v224, v46, v160
	v_exp_f32_e32 v203, v203
	v_mul_f32_e32 v204, s5, v224
	v_rcp_f32_e32 v202, v202
	v_add_f32_e32 v203, 1.0, v203
	v_mul_f32_e32 v183, v195, v183
	v_cvt_pk_bf16_f32 v184, v176, v177
	v_cvt_pk_bf16_f32 v185, v178, v179
	v_cvt_pk_bf16_f32 v186, v180, v181
	v_cvt_pk_bf16_f32 v187, v182, v183
	global_store_dwordx4 v[134:135], v[184:187], off
	v_lshl_add_u64 v[134:135], v[134:135], 0, s[6:7]
	v_mul_f32_e32 v225, v47, v160
	v_exp_f32_e32 v204, v204
	v_mul_f32_e32 v205, s5, v225
	v_rcp_f32_e32 v203, v203
	v_add_f32_e32 v204, 1.0, v204
	v_mul_f32_e32 v202, v222, v202
	v_mul_f32_e32 v226, v40, v160
	v_exp_f32_e32 v205, v205
	v_mul_f32_e32 v206, s5, v226
	v_rcp_f32_e32 v204, v204
	v_add_f32_e32 v205, 1.0, v205
	v_mul_f32_e32 v203, v223, v203
	v_mul_f32_e32 v227, v41, v160
	v_exp_f32_e32 v206, v206
	v_mul_f32_e32 v207, s5, v227
	v_rcp_f32_e32 v205, v205
	v_add_f32_e32 v206, 1.0, v206
	v_mul_f32_e32 v204, v224, v204
	v_mul_f32_e32 v232, v42, v160
	v_exp_f32_e32 v207, v207
	v_mul_f32_e32 v208, s5, v232
	v_rcp_f32_e32 v206, v206
	v_add_f32_e32 v207, 1.0, v207
	v_mul_f32_e32 v205, v225, v205
	v_mul_f32_e32 v233, v43, v160
	v_exp_f32_e32 v208, v208
	v_mul_f32_e32 v209, s5, v233
	v_rcp_f32_e32 v207, v207
	v_add_f32_e32 v208, 1.0, v208
	v_mul_f32_e32 v206, v226, v206
	v_mul_f32_e32 v188, v28, v158
	v_exp_f32_e32 v209, v209
	v_mul_f32_e32 v176, s5, v188
	v_rcp_f32_e32 v208, v208
	v_add_f32_e32 v209, 1.0, v209
	v_mul_f32_e32 v207, v227, v207
	v_mul_f32_e32 v189, v29, v158
	v_exp_f32_e32 v176, v176
	v_mul_f32_e32 v177, s5, v189
	v_rcp_f32_e32 v209, v209
	v_add_f32_e32 v176, 1.0, v176
	v_mul_f32_e32 v208, v232, v208
	v_mul_f32_e32 v190, v30, v158
	v_exp_f32_e32 v177, v177
	v_mul_f32_e32 v178, s5, v190
	v_rcp_f32_e32 v176, v176
	v_add_f32_e32 v177, 1.0, v177
	v_mul_f32_e32 v209, v233, v209
	v_cvt_pk_bf16_f32 v228, v202, v203
	v_cvt_pk_bf16_f32 v229, v204, v205
	v_cvt_pk_bf16_f32 v230, v206, v207
	v_cvt_pk_bf16_f32 v231, v208, v209
	global_store_dwordx4 v[134:135], v[228:231], off
	v_lshl_add_u64 v[134:135], v[134:135], 0, s[6:7]
	v_mul_f32_e32 v191, v31, v158
	v_exp_f32_e32 v178, v178
	v_mul_f32_e32 v179, s5, v191
	v_rcp_f32_e32 v177, v177
	v_add_f32_e32 v178, 1.0, v178
	v_mul_f32_e32 v176, v188, v176
	v_mul_f32_e32 v192, v24, v158
	v_exp_f32_e32 v179, v179
	v_mul_f32_e32 v180, s5, v192
	v_rcp_f32_e32 v178, v178
	v_add_f32_e32 v179, 1.0, v179
	v_mul_f32_e32 v177, v189, v177
	v_mul_f32_e32 v193, v25, v158
	v_exp_f32_e32 v180, v180
	v_mul_f32_e32 v181, s5, v193
	v_rcp_f32_e32 v179, v179
	v_add_f32_e32 v180, 1.0, v180
	v_mul_f32_e32 v178, v190, v178
	v_mul_f32_e32 v194, v26, v158
	v_exp_f32_e32 v181, v181
	v_mul_f32_e32 v182, s5, v194
	v_rcp_f32_e32 v180, v180
	v_add_f32_e32 v181, 1.0, v181
	v_mul_f32_e32 v179, v191, v179
	v_mul_f32_e32 v195, v27, v158
	v_exp_f32_e32 v182, v182
	v_mul_f32_e32 v183, s5, v195
	v_rcp_f32_e32 v181, v181
	v_add_f32_e32 v182, 1.0, v182
	v_mul_f32_e32 v180, v192, v180
	v_mul_f32_e32 v222, v12, v156
	v_exp_f32_e32 v183, v183
	v_mul_f32_e32 v202, s5, v222
	v_rcp_f32_e32 v182, v182
	v_add_f32_e32 v183, 1.0, v183
	v_mul_f32_e32 v181, v193, v181
	v_mul_f32_e32 v223, v13, v156
	v_exp_f32_e32 v202, v202
	v_mul_f32_e32 v203, s5, v223
	v_rcp_f32_e32 v183, v183
	v_add_f32_e32 v202, 1.0, v202
	v_mul_f32_e32 v182, v194, v182
	v_mul_f32_e32 v224, v14, v156
	v_exp_f32_e32 v203, v203
	v_mul_f32_e32 v204, s5, v224
	v_rcp_f32_e32 v202, v202
	v_add_f32_e32 v203, 1.0, v203
	v_mul_f32_e32 v183, v195, v183
	v_cvt_pk_bf16_f32 v184, v176, v177
	v_cvt_pk_bf16_f32 v185, v178, v179
	v_cvt_pk_bf16_f32 v186, v180, v181
	v_cvt_pk_bf16_f32 v187, v182, v183
	global_store_dwordx4 v[134:135], v[184:187], off
	v_lshl_add_u64 v[134:135], v[134:135], 0, s[6:7]
	v_mul_f32_e32 v225, v15, v156
	v_exp_f32_e32 v204, v204
	v_mul_f32_e32 v205, s5, v225
	v_rcp_f32_e32 v203, v203
	v_add_f32_e32 v204, 1.0, v204
	v_mul_f32_e32 v202, v222, v202
	v_mul_f32_e32 v226, v8, v156
	v_exp_f32_e32 v205, v205
	v_mul_f32_e32 v206, s5, v226
	v_rcp_f32_e32 v204, v204
	v_add_f32_e32 v205, 1.0, v205
	v_mul_f32_e32 v203, v223, v203
	v_mul_f32_e32 v227, v9, v156
	v_exp_f32_e32 v206, v206
	v_mul_f32_e32 v207, s5, v227
	v_rcp_f32_e32 v205, v205
	v_add_f32_e32 v206, 1.0, v206
	v_mul_f32_e32 v204, v224, v204
	v_mul_f32_e32 v232, v10, v156
	v_exp_f32_e32 v207, v207
	v_mul_f32_e32 v208, s5, v232
	v_rcp_f32_e32 v206, v206
	v_add_f32_e32 v207, 1.0, v207
	v_mul_f32_e32 v205, v225, v205
	v_mul_f32_e32 v233, v11, v156
	v_exp_f32_e32 v208, v208
	v_mul_f32_e32 v209, s5, v233
	v_rcp_f32_e32 v207, v207
	v_add_f32_e32 v208, 1.0, v208
	v_mul_f32_e32 v206, v226, v206
	v_exp_f32_e32 v209, v209
	v_rcp_f32_e32 v208, v208
	v_add_f32_e32 v209, 1.0, v209
	v_mul_f32_e32 v207, v227, v207
	v_rcp_f32_e32 v209, v209
	v_mul_f32_e32 v208, v232, v208
	v_mul_f32_e32 v209, v233, v209
	v_cvt_pk_bf16_f32 v228, v202, v203
	v_cvt_pk_bf16_f32 v229, v204, v205
	v_cvt_pk_bf16_f32 v230, v206, v207
	v_cvt_pk_bf16_f32 v231, v208, v209
	global_store_dwordx4 v[134:135], v[228:231], off
	s_branch .Lp2e_b0_done

; DI u32x4 pack8(const float* x) { u32x4 v; v.x = cvt_pk(x[0], x[1]); v.y = cvt_pk(x[2], x[3]); v.z = cvt_pk(x[4], x[5]); v.w = cvt_pk(x[6], x[7]); return v; }
; DI float sigmoidf_(float v) { return __builtin_amdgcn_rcpf(1.0f + __expf(-v)); }
;     DI void operator()(const f32x4 (&acc)[2][2][4][2], const Unit& u, int wr, int wc, int fr, int fq) const {
;     ...
;         for (int bj = 0; bj < 2; ++bj) {
;             const int colw = u.pn * BM + bj * HALF + wc * 32;
;             const int act = colw < C_SILU ? 0 : (colw < C_GATE ? 1 : 2);
; #pragma unroll
;             for (int ai = 0; ai < 2; ++ai)
; #pragma unroll
;                 for (int m = 0; m < 4; ++m) {
;                     float v[8];
; #pragma unroll
;                     for (int j = 0; j < 4; ++j) { v[j] = acc[ai][bj][m][0][j] * rstd[ai][m]; v[4 + j] = acc[ai][bj][m][1][j] * rstd[ai][m]; }
;                     if (act) {
; #pragma unroll
;                         for (int j = 0; j < 8; ++j) { const float sg = sigmoidf_(v[j]); v[j] = act == 1 ? v[j] * sg : sg; }
;                     }
;                     *(u32x4*)(O + (size_t)(row0 + ai * HALF + m * 16) * LDP + col0 + bj * HALF) = pack8(v);
;                 }
.Lp2e_b0_done:
	s_bitset1_b32 s8, 7
	v_mov_b64_e32 v[134:135], v[132:133]
	s_cmpk_lt_i32 s8, 0x1da0
	s_cbranch_scc1 .Lp2e_b1_act0
	s_cmpk_lt_i32 s8, 0x25a0
	s_cbranch_scc1 .Lp2e_b1_act1
	v_mul_f32_e32 v176, v116, v172
	v_mul_f32_e32 v176, s5, v176
	v_mul_f32_e32 v177, v117, v172
	v_exp_f32_e32 v176, v176
	v_mul_f32_e32 v177, s5, v177
	v_add_f32_e32 v176, 1.0, v176
	v_mul_f32_e32 v178, v118, v172
	v_exp_f32_e32 v177, v177
	v_mul_f32_e32 v178, s5, v178
	v_rcp_f32_e32 v176, v176
	v_add_f32_e32 v177, 1.0, v177
	v_mul_f32_e32 v179, v119, v172
	v_exp_f32_e32 v178, v178
	v_mul_f32_e32 v179, s5, v179
	v_rcp_f32_e32 v177, v177
	v_add_f32_e32 v178, 1.0, v178
	v_mul_f32_e32 v180, v112, v172
	v_exp_f32_e32 v179, v179
	v_mul_f32_e32 v180, s5, v180
	v_rcp_f32_e32 v178, v178
	v_add_f32_e32 v179, 1.0, v179
	v_mul_f32_e32 v181, v113, v172
	v_exp_f32_e32 v180, v180
	v_mul_f32_e32 v181, s5, v181
	v_rcp_f32_e32 v179, v179
	v_add_f32_e32 v180, 1.0, v180
	v_mul_f32_e32 v182, v114, v172
	v_exp_f32_e32 v181, v181
	v_mul_f32_e32 v182, s5, v182
	v_rcp_f32_e32 v180, v180
	v_add_f32_e32 v181, 1.0, v181
	v_mul_f32_e32 v183, v115, v172
	v_exp_f32_e32 v182, v182
	v_mul_f32_e32 v183, s5, v183
	v_rcp_f32_e32 v181, v181
	v_add_f32_e32 v182, 1.0, v182
	v_mul_f32_e32 v202, v100, v168
	v_exp_f32_e32 v183, v183
	v_mul_f32_e32 v202, s5, v202
	v_rcp_f32_e32 v182, v182
	v_add_f32_e32 v183, 1.0, v183
	v_mul_f32_e32 v203, v101, v168
	v_exp_f32_e32 v202, v202
	v_mul_f32_e32 v203, s5, v203
	v_rcp_f32_e32 v183, v183
	v_add_f32_e32 v202, 1.0, v202
	s_nop 0
	v_cvt_pk_bf16_f32 v184, v176, v177
	v_cvt_pk_bf16_f32 v185, v178, v179
	v_cvt_pk_bf16_f32 v186, v180, v181
	v_cvt_pk_bf16_f32 v187, v182, v183
	global_store_dwordx4 v[134:135], v[184:187], off offset:256
	v_lshl_add_u64 v[134:135], v[134:135], 0, s[6:7]
	v_mul_f32_e32 v204, v102, v168
	v_exp_f32_e32 v203, v203
	v_mul_f32_e32 v204, s5, v204
	v_rcp_f32_e32 v202, v202
	v_add_f32_e32 v203, 1.0, v203
	v_mul_f32_e32 v205, v103, v168
	v_exp_f32_e32 v204, v204
	v_mul_f32_e32 v205, s5, v205
	v_rcp_f32_e32 v203, v203
	v_add_f32_e32 v204, 1.0, v204
	v_mul_f32_e32 v206, v96, v168
	v_exp_f32_e32 v205, v205
	v_mul_f32_e32 v206, s5, v206
	v_rcp_f32_e32 v204, v204
	v_add_f32_e32 v205, 1.0, v205
	v_mul_f32_e32 v207, v97, v168
	v_exp_f32_e32 v206, v206
	v_mul_f32_e32 v207, s5, v207
	v_rcp_f32_e32 v205, v205
	v_add_f32_e32 v206, 1.0, v206
	v_mul_f32_e32 v208, v98, v168
	v_exp_f32_e32 v207, v207
	v_mul_f32_e32 v208, s5, v208
	v_rcp_f32_e32 v206, v206
	v_add_f32_e32 v207, 1.0, v207
	v_mul_f32_e32 v209, v99, v168
	v_exp_f32_e32 v208, v208
	v_mul_f32_e32 v209, s5, v209
	v_rcp_f32_e32 v207, v207
	v_add_f32_e32 v208, 1.0, v208
	v_mul_f32_e32 v176, v84, v166
	v_exp_f32_e32 v209, v209
	v_mul_f32_e32 v176, s5, v176
	v_rcp_f32_e32 v208, v208
	v_add_f32_e32 v209, 1.0, v209
	v_mul_f32_e32 v177, v85, v166
	v_exp_f32_e32 v176, v176
	v_mul_f32_e32 v177, s5, v177
	v_rcp_f32_e32 v209, v209
	v_add_f32_e32 v176, 1.0, v176
	s_nop 0
	v_cvt_pk_bf16_f32 v228, v202, v203
	v_cvt_pk_bf16_f32 v229, v204, v205
	v_cvt_pk_bf16_f32 v230, v206, v207
	v_cvt_pk_bf16_f32 v231, v208, v209
	global_store_dwordx4 v[134:135], v[228:231], off offset:256
	v_lshl_add_u64 v[134:135], v[134:135], 0, s[6:7]
	v_mul_f32_e32 v178, v86, v166
	v_exp_f32_e32 v177, v177
	v_mul_f32_e32 v178, s5, v178
	v_rcp_f32_e32 v176, v176
	v_add_f32_e32 v177, 1.0, v177
	v_mul_f32_e32 v179, v87, v166
	v_exp_f32_e32 v178, v178
	v_mul_f32_e32 v179, s5, v179
	v_rcp_f32_e32 v177, v177
	v_add_f32_e32 v178, 1.0, v178
	v_mul_f32_e32 v180, v80, v166
	v_exp_f32_e32 v179, v179
	v_mul_f32_e32 v180, s5, v180
	v_rcp_f32_e32 v178, v178
	v_add_f32_e32 v179, 1.0, v179
	v_mul_f32_e32 v181, v81, v166
	v_exp_f32_e32 v180, v180
	v_mul_f32_e32 v181, s5, v181
	v_rcp_f32_e32 v179, v179
	v_add_f32_e32 v180, 1.0, v180
	v_mul_f32_e32 v182, v82, v166
	v_exp_f32_e32 v181, v181
	v_mul_f32_e32 v182, s5, v182
	v_rcp_f32_e32 v180, v180
	v_add_f32_e32 v181, 1.0, v181
	v_mul_f32_e32 v183, v83, v166
	v_exp_f32_e32 v182, v182
	v_mul_f32_e32 v183, s5, v183
	v_rcp_f32_e32 v181, v181
	v_add_f32_e32 v182, 1.0, v182
	v_mul_f32_e32 v202, v68, v164
	v_exp_f32_e32 v183, v183
	v_mul_f32_e32 v202, s5, v202
	v_rcp_f32_e32 v182, v182
	v_add_f32_e32 v183, 1.0, v183
	v_mul_f32_e32 v203, v69, v164
	v_exp_f32_e32 v202, v202
	v_mul_f32_e32 v203, s5, v203
	v_rcp_f32_e32 v183, v183
	v_add_f32_e32 v202, 1.0, v202
	s_nop 0
	v_cvt_pk_bf16_f32 v184, v176, v177
	v_cvt_pk_bf16_f32 v185, v178, v179
	v_cvt_pk_bf16_f32 v186, v180, v181
	v_cvt_pk_bf16_f32 v187, v182, v183
	global_store_dwordx4 v[134:135], v[184:187], off offset:256
	v_lshl_add_u64 v[134:135], v[134:135], 0, s[6:7]
	v_mul_f32_e32 v204, v70, v164
	v_exp_f32_e32 v203, v203
	v_mul_f32_e32 v204, s5, v204
	v_rcp_f32_e32 v202, v202
	v_add_f32_e32 v203, 1.0, v203
	v_mul_f32_e32 v205, v71, v164
	v_exp_f32_e32 v204, v204
	v_mul_f32_e32 v205, s5, v205
	v_rcp_f32_e32 v203, v203
	v_add_f32_e32 v204, 1.0, v204
	v_mul_f32_e32 v206, v64, v164
	v_exp_f32_e32 v205, v205
	v_mul_f32_e32 v206, s5, v206
	v_rcp_f32_e32 v204, v204
	v_add_f32_e32 v205, 1.0, v205
	v_mul_f32_e32 v207, v65, v164
	v_exp_f32_e32 v206, v206
	v_mul_f32_e32 v207, s5, v207
	v_rcp_f32_e32 v205, v205
	v_add_f32_e32 v206, 1.0, v206
	v_mul_f32_e32 v208, v66, v164
	v_exp_f32_e32 v207, v207
	v_mul_f32_e32 v208, s5, v208
	v_rcp_f32_e32 v206, v206
	v_add_f32_e32 v207, 1.0, v207
	v_mul_f32_e32 v209, v67, v164
	v_exp_f32_e32 v208, v208
	v_mul_f32_e32 v209, s5, v209
	v_rcp_f32_e32 v207, v207
	v_add_f32_e32 v208, 1.0, v208
	v_mul_f32_e32 v176, v52, v162
	v_exp_f32_e32 v209, v209
	v_mul_f32_e32 v176, s5, v176
	v_rcp_f32_e32 v208, v208
	v_add_f32_e32 v209, 1.0, v209
; DI u32x4 pack8(const float* x) { u32x4 v; v.x = cvt_pk(x[0], x[1]); v.y = cvt_pk(x[2], x[3]); v.z = cvt_pk(x[4], x[5]); v.w = cvt_pk(x[6], x[7]); return v; }
; DI float sigmoidf_(float v) { return __builtin_amdgcn_rcpf(1.0f + __expf(-v)); }
;     DI void operator()(const f32x4 (&acc)[2][2][4][2], const Unit& u, int wr, int wc, int fr, int fq) const {
;     ...
; #pragma unroll
;         for (int bj = 0; bj < 2; ++bj) {
;             const int colw = u.pn * BM + bj * HALF + wc * 32;
;             const int act = colw < C_SILU ? 0 : (colw < C_GATE ? 1 : 2);
; #pragma unroll
;             for (int ai = 0; ai < 2; ++ai)
; #pragma unroll
;                 for (int m = 0; m < 4; ++m) {
;                     float v[8];
; #pragma unroll
;                     for (int j = 0; j < 4; ++j) { v[j] = acc[ai][bj][m][0][j] * rstd[ai][m]; v[4 + j] = acc[ai][bj][m][1][j] * rstd[ai][m]; }
;                     if (act) {
; #pragma unroll
;                         for (int j = 0; j < 8; ++j) { const float sg = sigmoidf_(v[j]); v[j] = act == 1 ? v[j] * sg : sg; }
;                     }
;                     *(u32x4*)(O + (size_t)(row0 + ai * HALF + m * 16) * LDP + col0 + bj * HALF) = pack8(v);
;                 }
	v_mul_f32_e32 v177, v53, v162
	v_exp_f32_e32 v176, v176
	v_mul_f32_e32 v177, s5, v177
	v_rcp_f32_e32 v209, v209
	v_add_f32_e32 v176, 1.0, v176
	s_nop 0
	v_cvt_pk_bf16_f32 v228, v202, v203
	v_cvt_pk_bf16_f32 v229, v204, v205
	v_cvt_pk_bf16_f32 v230, v206, v207
	v_cvt_pk_bf16_f32 v231, v208, v209
	global_store_dwordx4 v[134:135], v[228:231], off offset:256
	v_lshl_add_u64 v[134:135], v[134:135], 0, s[2:3]
	v_mul_f32_e32 v178, v54, v162
	v_exp_f32_e32 v177, v177
	v_mul_f32_e32 v178, s5, v178
	v_rcp_f32_e32 v176, v176
	v_add_f32_e32 v177, 1.0, v177
	v_mul_f32_e32 v179, v55, v162
	v_exp_f32_e32 v178, v178
	v_mul_f32_e32 v179, s5, v179
	v_rcp_f32_e32 v177, v177
	v_add_f32_e32 v178, 1.0, v178
	v_mul_f32_e32 v180, v48, v162
	v_exp_f32_e32 v179, v179
	v_mul_f32_e32 v180, s5, v180
	v_rcp_f32_e32 v178, v178
	v_add_f32_e32 v179, 1.0, v179
	v_mul_f32_e32 v181, v49, v162
	v_exp_f32_e32 v180, v180
	v_mul_f32_e32 v181, s5, v181
	v_rcp_f32_e32 v179, v179
	v_add_f32_e32 v180, 1.0, v180
	v_mul_f32_e32 v182, v50, v162
	v_exp_f32_e32 v181, v181
	v_mul_f32_e32 v182, s5, v182
	v_rcp_f32_e32 v180, v180
	v_add_f32_e32 v181, 1.0, v181
	v_mul_f32_e32 v183, v51, v162
	v_exp_f32_e32 v182, v182
	v_mul_f32_e32 v183, s5, v183
	v_rcp_f32_e32 v181, v181
	v_add_f32_e32 v182, 1.0, v182
	v_mul_f32_e32 v202, v36, v160
	v_exp_f32_e32 v183, v183
	v_mul_f32_e32 v202, s5, v202
	v_rcp_f32_e32 v182, v182
	v_add_f32_e32 v183, 1.0, v183
	v_mul_f32_e32 v203, v37, v160
	v_exp_f32_e32 v202, v202
	v_mul_f32_e32 v203, s5, v203
	v_rcp_f32_e32 v183, v183
	v_add_f32_e32 v202, 1.0, v202
	s_nop 0
	v_cvt_pk_bf16_f32 v184, v176, v177
	v_cvt_pk_bf16_f32 v185, v178, v179
	v_cvt_pk_bf16_f32 v186, v180, v181
	v_cvt_pk_bf16_f32 v187, v182, v183
	global_store_dwordx4 v[134:135], v[184:187], off offset:256
	v_lshl_add_u64 v[134:135], v[134:135], 0, s[6:7]
	v_mul_f32_e32 v204, v38, v160
	v_exp_f32_e32 v203, v203
	v_mul_f32_e32 v204, s5, v204
	v_rcp_f32_e32 v202, v202
	v_add_f32_e32 v203, 1.0, v203
	v_mul_f32_e32 v205, v39, v160
	v_exp_f32_e32 v204, v204
	v_mul_f32_e32 v205, s5, v205
	v_rcp_f32_e32 v203, v203
	v_add_f32_e32 v204, 1.0, v204
	v_mul_f32_e32 v206, v32, v160
	v_exp_f32_e32 v205, v205
	v_mul_f32_e32 v206, s5, v206
	v_rcp_f32_e32 v204, v204
	v_add_f32_e32 v205, 1.0, v205
	v_mul_f32_e32 v207, v33, v160
	v_exp_f32_e32 v206, v206
	v_mul_f32_e32 v207, s5, v207
	v_rcp_f32_e32 v205, v205
	v_add_f32_e32 v206, 1.0, v206
	v_mul_f32_e32 v208, v34, v160
	v_exp_f32_e32 v207, v207
	v_mul_f32_e32 v208, s5, v208
	v_rcp_f32_e32 v206, v206
	v_add_f32_e32 v207, 1.0, v207
	v_mul_f32_e32 v209, v35, v160
	v_exp_f32_e32 v208, v208
	v_mul_f32_e32 v209, s5, v209
	v_rcp_f32_e32 v207, v207
	v_add_f32_e32 v208, 1.0, v208
	v_mul_f32_e32 v176, v20, v158
	v_exp_f32_e32 v209, v209
	v_mul_f32_e32 v176, s5, v176
	v_rcp_f32_e32 v208, v208
	v_add_f32_e32 v209, 1.0, v209
	v_mul_f32_e32 v177, v21, v158
	v_exp_f32_e32 v176, v176
	v_mul_f32_e32 v177, s5, v177
	v_rcp_f32_e32 v209, v209
	v_add_f32_e32 v176, 1.0, v176
	s_nop 0
	v_cvt_pk_bf16_f32 v228, v202, v203
	v_cvt_pk_bf16_f32 v229, v204, v205
	v_cvt_pk_bf16_f32 v230, v206, v207
	v_cvt_pk_bf16_f32 v231, v208, v209
	global_store_dwordx4 v[134:135], v[228:231], off offset:256
	v_lshl_add_u64 v[134:135], v[134:135], 0, s[6:7]
	v_mul_f32_e32 v178, v22, v158
	v_exp_f32_e32 v177, v177
	v_mul_f32_e32 v178, s5, v178
	v_rcp_f32_e32 v176, v176
	v_add_f32_e32 v177, 1.0, v177
	v_mul_f32_e32 v179, v23, v158
	v_exp_f32_e32 v178, v178
	v_mul_f32_e32 v179, s5, v179
	v_rcp_f32_e32 v177, v177
	v_add_f32_e32 v178, 1.0, v178
	v_mul_f32_e32 v180, v16, v158
	v_exp_f32_e32 v179, v179
	v_mul_f32_e32 v180, s5, v180
	v_rcp_f32_e32 v178, v178
	v_add_f32_e32 v179, 1.0, v179
	v_mul_f32_e32 v181, v17, v158
	v_exp_f32_e32 v180, v180
	v_mul_f32_e32 v181, s5, v181
	v_rcp_f32_e32 v179, v179
	v_add_f32_e32 v180, 1.0, v180
	v_mul_f32_e32 v182, v18, v158
	v_exp_f32_e32 v181, v181
	v_mul_f32_e32 v182, s5, v182
	v_rcp_f32_e32 v180, v180
	v_add_f32_e32 v181, 1.0, v181
	v_mul_f32_e32 v183, v19, v158
	v_exp_f32_e32 v182, v182
	v_mul_f32_e32 v183, s5, v183
	v_rcp_f32_e32 v181, v181
	v_add_f32_e32 v182, 1.0, v182
	v_mul_f32_e32 v202, v4, v156
	v_exp_f32_e32 v183, v183
	v_mul_f32_e32 v202, s5, v202
	v_rcp_f32_e32 v182, v182
	v_add_f32_e32 v183, 1.0, v183
	v_mul_f32_e32 v203, v5, v156
	v_exp_f32_e32 v202, v202
	v_mul_f32_e32 v203, s5, v203
	v_rcp_f32_e32 v183, v183
	v_add_f32_e32 v202, 1.0, v202
	s_nop 0
	v_cvt_pk_bf16_f32 v184, v176, v177
	v_cvt_pk_bf16_f32 v185, v178, v179
	v_cvt_pk_bf16_f32 v186, v180, v181
	v_cvt_pk_bf16_f32 v187, v182, v183
	global_store_dwordx4 v[134:135], v[184:187], off offset:256
	v_lshl_add_u64 v[134:135], v[134:135], 0, s[6:7]
	v_mul_f32_e32 v204, v6, v156
	v_exp_f32_e32 v203, v203
	v_mul_f32_e32 v204, s5, v204
	v_rcp_f32_e32 v202, v202
	v_add_f32_e32 v203, 1.0, v203
	v_mul_f32_e32 v205, v7, v156
	v_exp_f32_e32 v204, v204
	v_mul_f32_e32 v205, s5, v205
	v_rcp_f32_e32 v203, v203
	v_add_f32_e32 v204, 1.0, v204
	v_mul_f32_e32 v206, v0, v156
	v_exp_f32_e32 v205, v205
	v_mul_f32_e32 v206, s5, v206
	v_rcp_f32_e32 v204, v204
	v_add_f32_e32 v205, 1.0, v205
	v_mul_f32_e32 v207, v1, v156
	v_exp_f32_e32 v206, v206
	v_mul_f32_e32 v207, s5, v207
	v_rcp_f32_e32 v205, v205
	v_add_f32_e32 v206, 1.0, v206
	v_mul_f32_e32 v208, v2, v156
	v_exp_f32_e32 v207, v207
	v_mul_f32_e32 v208, s5, v208
	v_rcp_f32_e32 v206, v206
	v_add_f32_e32 v207, 1.0, v207
	v_mul_f32_e32 v209, v3, v156
	v_exp_f32_e32 v208, v208
	v_mul_f32_e32 v209, s5, v209
	v_rcp_f32_e32 v207, v207
	v_add_f32_e32 v208, 1.0, v208
	v_exp_f32_e32 v209, v209
	v_rcp_f32_e32 v208, v208
	v_add_f32_e32 v209, 1.0, v209
	v_rcp_f32_e32 v209, v209
	s_nop 0
	v_cvt_pk_bf16_f32 v228, v202, v203
	v_cvt_pk_bf16_f32 v229, v204, v205
	v_cvt_pk_bf16_f32 v230, v206, v207
	v_cvt_pk_bf16_f32 v231, v208, v209
	global_store_dwordx4 v[134:135], v[228:231], off offset:256
	s_branch .Lp2e_b1_done
; DI u32x4 pack8(const float* x) { u32x4 v; v.x = cvt_pk(x[0], x[1]); v.y = cvt_pk(x[2], x[3]); v.z = cvt_pk(x[4], x[5]); v.w = cvt_pk(x[6], x[7]); return v; }
; DI float sigmoidf_(float v) { return __builtin_amdgcn_rcpf(1.0f + __expf(-v)); }
;     DI void operator()(const f32x4 (&acc)[2][2][4][2], const Unit& u, int wr, int wc, int fr, int fq) const {
;     ...
;             for (int ai = 0; ai < 2; ++ai)
; #pragma unroll
;                 for (int m = 0; m < 4; ++m) {
;                     float v[8];
; #pragma unroll
;                     for (int j = 0; j < 4; ++j) { v[j] = acc[ai][bj][m][0][j] * rstd[ai][m]; v[4 + j] = acc[ai][bj][m][1][j] * rstd[ai][m]; }
;                     if (act) {
; #pragma unroll
;                         for (int j = 0; j < 8; ++j) { const float sg = sigmoidf_(v[j]); v[j] = act == 1 ? v[j] * sg : sg; }
;                     }
;                     *(u32x4*)(O + (size_t)(row0 + ai * HALF + m * 16) * LDP + col0 + bj * HALF) = pack8(v);
;                 }
.Lp2e_b1_act1:
	v_mul_f32_e32 v188, v116, v172
	v_mul_f32_e32 v176, s5, v188
	v_mul_f32_e32 v189, v117, v172
	v_exp_f32_e32 v176, v176
	v_mul_f32_e32 v177, s5, v189
	v_add_f32_e32 v176, 1.0, v176
	v_mul_f32_e32 v190, v118, v172
	v_exp_f32_e32 v177, v177
	v_mul_f32_e32 v178, s5, v190
	v_rcp_f32_e32 v176, v176
	v_add_f32_e32 v177, 1.0, v177
	v_mul_f32_e32 v191, v119, v172
	v_exp_f32_e32 v178, v178
	v_mul_f32_e32 v179, s5, v191
	v_rcp_f32_e32 v177, v177
	v_add_f32_e32 v178, 1.0, v178
	v_mul_f32_e32 v176, v188, v176
	v_mul_f32_e32 v192, v112, v172
	v_exp_f32_e32 v179, v179
	v_mul_f32_e32 v180, s5, v192
	v_rcp_f32_e32 v178, v178
	v_add_f32_e32 v179, 1.0, v179
	v_mul_f32_e32 v177, v189, v177
	v_mul_f32_e32 v193, v113, v172
	v_exp_f32_e32 v180, v180
	v_mul_f32_e32 v181, s5, v193
	v_rcp_f32_e32 v179, v179
	v_add_f32_e32 v180, 1.0, v180
	v_mul_f32_e32 v178, v190, v178
	v_mul_f32_e32 v194, v114, v172
	v_exp_f32_e32 v181, v181
	v_mul_f32_e32 v182, s5, v194
	v_rcp_f32_e32 v180, v180
	v_add_f32_e32 v181, 1.0, v181
	v_mul_f32_e32 v179, v191, v179
	v_mul_f32_e32 v195, v115, v172
	v_exp_f32_e32 v182, v182
	v_mul_f32_e32 v183, s5, v195
	v_rcp_f32_e32 v181, v181
	v_add_f32_e32 v182, 1.0, v182
	v_mul_f32_e32 v180, v192, v180
	v_mul_f32_e32 v222, v100, v168
	v_exp_f32_e32 v183, v183
	v_mul_f32_e32 v202, s5, v222
	v_rcp_f32_e32 v182, v182
	v_add_f32_e32 v183, 1.0, v183
	v_mul_f32_e32 v181, v193, v181
	v_mul_f32_e32 v223, v101, v168
	v_exp_f32_e32 v202, v202
	v_mul_f32_e32 v203, s5, v223
	v_rcp_f32_e32 v183, v183
	v_add_f32_e32 v202, 1.0, v202
	v_mul_f32_e32 v182, v194, v182
	v_mul_f32_e32 v224, v102, v168
	v_exp_f32_e32 v203, v203
	v_mul_f32_e32 v204, s5, v224
	v_rcp_f32_e32 v202, v202
	v_add_f32_e32 v203, 1.0, v203
	v_mul_f32_e32 v183, v195, v183
	v_cvt_pk_bf16_f32 v184, v176, v177
	v_cvt_pk_bf16_f32 v185, v178, v179
	v_cvt_pk_bf16_f32 v186, v180, v181
	v_cvt_pk_bf16_f32 v187, v182, v183
	global_store_dwordx4 v[134:135], v[184:187], off offset:256
	v_lshl_add_u64 v[134:135], v[134:135], 0, s[6:7]
	v_mul_f32_e32 v225, v103, v168
	v_exp_f32_e32 v204, v204
	v_mul_f32_e32 v205, s5, v225
	v_rcp_f32_e32 v203, v203
	v_add_f32_e32 v204, 1.0, v204
	v_mul_f32_e32 v202, v222, v202
	v_mul_f32_e32 v226, v96, v168
	v_exp_f32_e32 v205, v205
	v_mul_f32_e32 v206, s5, v226
	v_rcp_f32_e32 v204, v204
	v_add_f32_e32 v205, 1.0, v205
	v_mul_f32_e32 v203, v223, v203
	v_mul_f32_e32 v227, v97, v168
	v_exp_f32_e32 v206, v206
	v_mul_f32_e32 v207, s5, v227
	v_rcp_f32_e32 v205, v205
	v_add_f32_e32 v206, 1.0, v206
	v_mul_f32_e32 v204, v224, v204
	v_mul_f32_e32 v232, v98, v168
	v_exp_f32_e32 v207, v207
	v_mul_f32_e32 v208, s5, v232
	v_rcp_f32_e32 v206, v206
	v_add_f32_e32 v207, 1.0, v207
	v_mul_f32_e32 v205, v225, v205
	v_mul_f32_e32 v233, v99, v168
	v_exp_f32_e32 v208, v208
	v_mul_f32_e32 v209, s5, v233
	v_rcp_f32_e32 v207, v207
	v_add_f32_e32 v208, 1.0, v208
	v_mul_f32_e32 v206, v226, v206
	v_mul_f32_e32 v188, v84, v166
	v_exp_f32_e32 v209, v209
	v_mul_f32_e32 v176, s5, v188
	v_rcp_f32_e32 v208, v208
	v_add_f32_e32 v209, 1.0, v209
	v_mul_f32_e32 v207, v227, v207
	v_mul_f32_e32 v189, v85, v166
	v_exp_f32_e32 v176, v176
	v_mul_f32_e32 v177, s5, v189
	v_rcp_f32_e32 v209, v209
	v_add_f32_e32 v176, 1.0, v176
	v_mul_f32_e32 v208, v232, v208
	v_mul_f32_e32 v190, v86, v166
	v_exp_f32_e32 v177, v177
	v_mul_f32_e32 v178, s5, v190
	v_rcp_f32_e32 v176, v176
	v_add_f32_e32 v177, 1.0, v177
	v_mul_f32_e32 v209, v233, v209
	v_cvt_pk_bf16_f32 v228, v202, v203
	v_cvt_pk_bf16_f32 v229, v204, v205
	v_cvt_pk_bf16_f32 v230, v206, v207
	v_cvt_pk_bf16_f32 v231, v208, v209
	global_store_dwordx4 v[134:135], v[228:231], off offset:256
	v_lshl_add_u64 v[134:135], v[134:135], 0, s[6:7]
	v_mul_f32_e32 v191, v87, v166
	v_exp_f32_e32 v178, v178
	v_mul_f32_e32 v179, s5, v191
	v_rcp_f32_e32 v177, v177
	v_add_f32_e32 v178, 1.0, v178
	v_mul_f32_e32 v176, v188, v176
	v_mul_f32_e32 v192, v80, v166
	v_exp_f32_e32 v179, v179
	v_mul_f32_e32 v180, s5, v192
	v_rcp_f32_e32 v178, v178
	v_add_f32_e32 v179, 1.0, v179
	v_mul_f32_e32 v177, v189, v177
	v_mul_f32_e32 v193, v81, v166
	v_exp_f32_e32 v180, v180
	v_mul_f32_e32 v181, s5, v193
	v_rcp_f32_e32 v179, v179
	v_add_f32_e32 v180, 1.0, v180
	v_mul_f32_e32 v178, v190, v178
	v_mul_f32_e32 v194, v82, v166
	v_exp_f32_e32 v181, v181
	v_mul_f32_e32 v182, s5, v194
	v_rcp_f32_e32 v180, v180
	v_add_f32_e32 v181, 1.0, v181
	v_mul_f32_e32 v179, v191, v179
	v_mul_f32_e32 v195, v83, v166
	v_exp_f32_e32 v182, v182
	v_mul_f32_e32 v183, s5, v195
	v_rcp_f32_e32 v181, v181
	v_add_f32_e32 v182, 1.0, v182
	v_mul_f32_e32 v180, v192, v180
	v_mul_f32_e32 v222, v68, v164
	v_exp_f32_e32 v183, v183
	v_mul_f32_e32 v202, s5, v222
	v_rcp_f32_e32 v182, v182
	v_add_f32_e32 v183, 1.0, v183
	v_mul_f32_e32 v181, v193, v181
	v_mul_f32_e32 v223, v69, v164
	v_exp_f32_e32 v202, v202
	v_mul_f32_e32 v203, s5, v223
	v_rcp_f32_e32 v183, v183
	v_add_f32_e32 v202, 1.0, v202
	v_mul_f32_e32 v182, v194, v182
	v_mul_f32_e32 v224, v70, v164
	v_exp_f32_e32 v203, v203
	v_mul_f32_e32 v204, s5, v224
	v_rcp_f32_e32 v202, v202
	v_add_f32_e32 v203, 1.0, v203
	v_mul_f32_e32 v183, v195, v183
	v_cvt_pk_bf16_f32 v184, v176, v177
	v_cvt_pk_bf16_f32 v185, v178, v179
	v_cvt_pk_bf16_f32 v186, v180, v181
	v_cvt_pk_bf16_f32 v187, v182, v183
	global_store_dwordx4 v[134:135], v[184:187], off offset:256
	v_lshl_add_u64 v[134:135], v[134:135], 0, s[6:7]
	v_mul_f32_e32 v225, v71, v164
	v_exp_f32_e32 v204, v204
	v_mul_f32_e32 v205, s5, v225
	v_rcp_f32_e32 v203, v203
	v_add_f32_e32 v204, 1.0, v204
	v_mul_f32_e32 v202, v222, v202
	v_mul_f32_e32 v226, v64, v164
	v_exp_f32_e32 v205, v205
	v_mul_f32_e32 v206, s5, v226
	v_rcp_f32_e32 v204, v204
; DI u32x4 pack8(const float* x) { u32x4 v; v.x = cvt_pk(x[0], x[1]); v.y = cvt_pk(x[2], x[3]); v.z = cvt_pk(x[4], x[5]); v.w = cvt_pk(x[6], x[7]); return v; }
; DI float sigmoidf_(float v) { return __builtin_amdgcn_rcpf(1.0f + __expf(-v)); }
;     DI void operator()(const f32x4 (&acc)[2][2][4][2], const Unit& u, int wr, int wc, int fr, int fq) const {
;     ...
;             for (int ai = 0; ai < 2; ++ai)
; #pragma unroll
;                 for (int m = 0; m < 4; ++m) {
;                     float v[8];
; #pragma unroll
;                     for (int j = 0; j < 4; ++j) { v[j] = acc[ai][bj][m][0][j] * rstd[ai][m]; v[4 + j] = acc[ai][bj][m][1][j] * rstd[ai][m]; }
;                     if (act) {
; #pragma unroll
;                         for (int j = 0; j < 8; ++j) { const float sg = sigmoidf_(v[j]); v[j] = act == 1 ? v[j] * sg : sg; }
;                     }
;                     *(u32x4*)(O + (size_t)(row0 + ai * HALF + m * 16) * LDP + col0 + bj * HALF) = pack8(v);
;                 }
	v_add_f32_e32 v205, 1.0, v205
	v_mul_f32_e32 v203, v223, v203
	v_mul_f32_e32 v227, v65, v164
	v_exp_f32_e32 v206, v206
	v_mul_f32_e32 v207, s5, v227
	v_rcp_f32_e32 v205, v205
	v_add_f32_e32 v206, 1.0, v206
	v_mul_f32_e32 v204, v224, v204
	v_mul_f32_e32 v232, v66, v164
	v_exp_f32_e32 v207, v207
	v_mul_f32_e32 v208, s5, v232
	v_rcp_f32_e32 v206, v206
	v_add_f32_e32 v207, 1.0, v207
	v_mul_f32_e32 v205, v225, v205
	v_mul_f32_e32 v233, v67, v164
	v_exp_f32_e32 v208, v208
	v_mul_f32_e32 v209, s5, v233
	v_rcp_f32_e32 v207, v207
	v_add_f32_e32 v208, 1.0, v208
	v_mul_f32_e32 v206, v226, v206
	v_mul_f32_e32 v188, v52, v162
	v_exp_f32_e32 v209, v209
	v_mul_f32_e32 v176, s5, v188
	v_rcp_f32_e32 v208, v208
	v_add_f32_e32 v209, 1.0, v209
	v_mul_f32_e32 v207, v227, v207
	v_mul_f32_e32 v189, v53, v162
	v_exp_f32_e32 v176, v176
	v_mul_f32_e32 v177, s5, v189
	v_rcp_f32_e32 v209, v209
	v_add_f32_e32 v176, 1.0, v176
	v_mul_f32_e32 v208, v232, v208
	v_mul_f32_e32 v190, v54, v162
	v_exp_f32_e32 v177, v177
	v_mul_f32_e32 v178, s5, v190
	v_rcp_f32_e32 v176, v176
	v_add_f32_e32 v177, 1.0, v177
	v_mul_f32_e32 v209, v233, v209
	v_cvt_pk_bf16_f32 v228, v202, v203
	v_cvt_pk_bf16_f32 v229, v204, v205
	v_cvt_pk_bf16_f32 v230, v206, v207
	v_cvt_pk_bf16_f32 v231, v208, v209
	global_store_dwordx4 v[134:135], v[228:231], off offset:256
	v_lshl_add_u64 v[134:135], v[134:135], 0, s[2:3]
	v_mul_f32_e32 v191, v55, v162
	v_exp_f32_e32 v178, v178
	v_mul_f32_e32 v179, s5, v191
	v_rcp_f32_e32 v177, v177
	v_add_f32_e32 v178, 1.0, v178
	v_mul_f32_e32 v176, v188, v176
	v_mul_f32_e32 v192, v48, v162
	v_exp_f32_e32 v179, v179
	v_mul_f32_e32 v180, s5, v192
	v_rcp_f32_e32 v178, v178
	v_add_f32_e32 v179, 1.0, v179
	v_mul_f32_e32 v177, v189, v177
	v_mul_f32_e32 v193, v49, v162
	v_exp_f32_e32 v180, v180
	v_mul_f32_e32 v181, s5, v193
	v_rcp_f32_e32 v179, v179
	v_add_f32_e32 v180, 1.0, v180
	v_mul_f32_e32 v178, v190, v178
	v_mul_f32_e32 v194, v50, v162
	v_exp_f32_e32 v181, v181
	v_mul_f32_e32 v182, s5, v194
	v_rcp_f32_e32 v180, v180
	v_add_f32_e32 v181, 1.0, v181
	v_mul_f32_e32 v179, v191, v179
	v_mul_f32_e32 v195, v51, v162
	v_exp_f32_e32 v182, v182
	v_mul_f32_e32 v183, s5, v195
	v_rcp_f32_e32 v181, v181
	v_add_f32_e32 v182, 1.0, v182
	v_mul_f32_e32 v180, v192, v180
	v_mul_f32_e32 v222, v36, v160
	v_exp_f32_e32 v183, v183
	v_mul_f32_e32 v202, s5, v222
	v_rcp_f32_e32 v182, v182
	v_add_f32_e32 v183, 1.0, v183
	v_mul_f32_e32 v181, v193, v181
	v_mul_f32_e32 v223, v37, v160
	v_exp_f32_e32 v202, v202
	v_mul_f32_e32 v203, s5, v223
	v_rcp_f32_e32 v183, v183
	v_add_f32_e32 v202, 1.0, v202
	v_mul_f32_e32 v182, v194, v182
	v_mul_f32_e32 v224, v38, v160
	v_exp_f32_e32 v203, v203
	v_mul_f32_e32 v204, s5, v224
	v_rcp_f32_e32 v202, v202
	v_add_f32_e32 v203, 1.0, v203
	v_mul_f32_e32 v183, v195, v183
	v_cvt_pk_bf16_f32 v184, v176, v177
	v_cvt_pk_bf16_f32 v185, v178, v179
	v_cvt_pk_bf16_f32 v186, v180, v181
	v_cvt_pk_bf16_f32 v187, v182, v183
	global_store_dwordx4 v[134:135], v[184:187], off offset:256
	v_lshl_add_u64 v[134:135], v[134:135], 0, s[6:7]
	v_mul_f32_e32 v225, v39, v160
	v_exp_f32_e32 v204, v204
	v_mul_f32_e32 v205, s5, v225
	v_rcp_f32_e32 v203, v203
	v_add_f32_e32 v204, 1.0, v204
	v_mul_f32_e32 v202, v222, v202
	v_mul_f32_e32 v226, v32, v160
	v_exp_f32_e32 v205, v205
	v_mul_f32_e32 v206, s5, v226
	v_rcp_f32_e32 v204, v204
	v_add_f32_e32 v205, 1.0, v205
	v_mul_f32_e32 v203, v223, v203
	v_mul_f32_e32 v227, v33, v160
	v_exp_f32_e32 v206, v206
	v_mul_f32_e32 v207, s5, v227
	v_rcp_f32_e32 v205, v205
	v_add_f32_e32 v206, 1.0, v206
	v_mul_f32_e32 v204, v224, v204
	v_mul_f32_e32 v232, v34, v160
	v_exp_f32_e32 v207, v207
	v_mul_f32_e32 v208, s5, v232
	v_rcp_f32_e32 v206, v206
	v_add_f32_e32 v207, 1.0, v207
	v_mul_f32_e32 v205, v225, v205
	v_mul_f32_e32 v233, v35, v160
	v_exp_f32_e32 v208, v208
	v_mul_f32_e32 v209, s5, v233
; DI u32x4 pack8(const float* x) { u32x4 v; v.x = cvt_pk(x[0], x[1]); v.y = cvt_pk(x[2], x[3]); v.z = cvt_pk(x[4], x[5]); v.w = cvt_pk(x[6], x[7]); return v; }
; DI float sigmoidf_(float v) { return __builtin_amdgcn_rcpf(1.0f + __expf(-v)); }
;     DI void operator()(const f32x4 (&acc)[2][2][4][2], const Unit& u, int wr, int wc, int fr, int fq) const {
;     ...
;             for (int ai = 0; ai < 2; ++ai)
; #pragma unroll
;                 for (int m = 0; m < 4; ++m) {
;                     float v[8];
; #pragma unroll
;                     for (int j = 0; j < 4; ++j) { v[j] = acc[ai][bj][m][0][j] * rstd[ai][m]; v[4 + j] = acc[ai][bj][m][1][j] * rstd[ai][m]; }
;                     if (act) {
; #pragma unroll
;                         for (int j = 0; j < 8; ++j) { const float sg = sigmoidf_(v[j]); v[j] = act == 1 ? v[j] * sg : sg; }
;                     }
;                     *(u32x4*)(O + (size_t)(row0 + ai * HALF + m * 16) * LDP + col0 + bj * HALF) = pack8(v);
;                 }
	v_rcp_f32_e32 v207, v207
	v_add_f32_e32 v208, 1.0, v208
	v_mul_f32_e32 v206, v226, v206
	v_mul_f32_e32 v188, v20, v158
	v_exp_f32_e32 v209, v209
	v_mul_f32_e32 v176, s5, v188
	v_rcp_f32_e32 v208, v208
	v_add_f32_e32 v209, 1.0, v209
	v_mul_f32_e32 v207, v227, v207
	v_mul_f32_e32 v189, v21, v158
	v_exp_f32_e32 v176, v176
	v_mul_f32_e32 v177, s5, v189
	v_rcp_f32_e32 v209, v209
	v_add_f32_e32 v176, 1.0, v176
	v_mul_f32_e32 v208, v232, v208
	v_mul_f32_e32 v190, v22, v158
	v_exp_f32_e32 v177, v177
	v_mul_f32_e32 v178, s5, v190
	v_rcp_f32_e32 v176, v176
	v_add_f32_e32 v177, 1.0, v177
	v_mul_f32_e32 v209, v233, v209
	v_cvt_pk_bf16_f32 v228, v202, v203
	v_cvt_pk_bf16_f32 v229, v204, v205
	v_cvt_pk_bf16_f32 v230, v206, v207
	v_cvt_pk_bf16_f32 v231, v208, v209
	global_store_dwordx4 v[134:135], v[228:231], off offset:256
	v_lshl_add_u64 v[134:135], v[134:135], 0, s[6:7]
	v_mul_f32_e32 v191, v23, v158
	v_exp_f32_e32 v178, v178
	v_mul_f32_e32 v179, s5, v191
	v_rcp_f32_e32 v177, v177
	v_add_f32_e32 v178, 1.0, v178
	v_mul_f32_e32 v176, v188, v176
	v_mul_f32_e32 v192, v16, v158
	v_exp_f32_e32 v179, v179
	v_mul_f32_e32 v180, s5, v192
	v_rcp_f32_e32 v178, v178
	v_add_f32_e32 v179, 1.0, v179
	v_mul_f32_e32 v177, v189, v177
	v_mul_f32_e32 v193, v17, v158
	v_exp_f32_e32 v180, v180
	v_mul_f32_e32 v181, s5, v193
	v_rcp_f32_e32 v179, v179
	v_add_f32_e32 v180, 1.0, v180
	v_mul_f32_e32 v178, v190, v178
	v_mul_f32_e32 v194, v18, v158
	v_exp_f32_e32 v181, v181
	v_mul_f32_e32 v182, s5, v194
	v_rcp_f32_e32 v180, v180
	v_add_f32_e32 v181, 1.0, v181
	v_mul_f32_e32 v179, v191, v179
	v_mul_f32_e32 v195, v19, v158
	v_exp_f32_e32 v182, v182
	v_mul_f32_e32 v183, s5, v195
	v_rcp_f32_e32 v181, v181
	v_add_f32_e32 v182, 1.0, v182
	v_mul_f32_e32 v180, v192, v180
	v_mul_f32_e32 v222, v4, v156
	v_exp_f32_e32 v183, v183
	v_mul_f32_e32 v202, s5, v222
	v_rcp_f32_e32 v182, v182
	v_add_f32_e32 v183, 1.0, v183
	v_mul_f32_e32 v181, v193, v181
	v_mul_f32_e32 v223, v5, v156
	v_exp_f32_e32 v202, v202
	v_mul_f32_e32 v203, s5, v223
	v_rcp_f32_e32 v183, v183
	v_add_f32_e32 v202, 1.0, v202
	v_mul_f32_e32 v182, v194, v182
	v_mul_f32_e32 v224, v6, v156
	v_exp_f32_e32 v203, v203
	v_mul_f32_e32 v204, s5, v224
	v_rcp_f32_e32 v202, v202
	v_add_f32_e32 v203, 1.0, v203
	v_mul_f32_e32 v183, v195, v183
	v_cvt_pk_bf16_f32 v184, v176, v177
	v_cvt_pk_bf16_f32 v185, v178, v179
	v_cvt_pk_bf16_f32 v186, v180, v181
	v_cvt_pk_bf16_f32 v187, v182, v183
	global_store_dwordx4 v[134:135], v[184:187], off offset:256
	v_lshl_add_u64 v[134:135], v[134:135], 0, s[6:7]
	v_mul_f32_e32 v225, v7, v156
	v_exp_f32_e32 v204, v204
	v_mul_f32_e32 v205, s5, v225
	v_rcp_f32_e32 v203, v203
	v_add_f32_e32 v204, 1.0, v204
	v_mul_f32_e32 v202, v222, v202
	v_mul_f32_e32 v226, v0, v156
	v_exp_f32_e32 v205, v205
	v_mul_f32_e32 v206, s5, v226
	v_rcp_f32_e32 v204, v204
	v_add_f32_e32 v205, 1.0, v205
	v_mul_f32_e32 v203, v223, v203
	v_mul_f32_e32 v227, v1, v156
	v_exp_f32_e32 v206, v206
	v_mul_f32_e32 v207, s5, v227
	v_rcp_f32_e32 v205, v205
	v_add_f32_e32 v206, 1.0, v206
	v_mul_f32_e32 v204, v224, v204
	v_mul_f32_e32 v232, v2, v156
	v_exp_f32_e32 v207, v207
	v_mul_f32_e32 v208, s5, v232
	v_rcp_f32_e32 v206, v206
	v_add_f32_e32 v207, 1.0, v207
	v_mul_f32_e32 v205, v225, v205
	v_mul_f32_e32 v233, v3, v156
	v_exp_f32_e32 v208, v208
	v_mul_f32_e32 v209, s5, v233
	v_rcp_f32_e32 v207, v207
	v_add_f32_e32 v208, 1.0, v208
	v_mul_f32_e32 v206, v226, v206
	v_exp_f32_e32 v209, v209
	v_rcp_f32_e32 v208, v208
	v_add_f32_e32 v209, 1.0, v209
	v_mul_f32_e32 v207, v227, v207
	v_rcp_f32_e32 v209, v209
	v_mul_f32_e32 v208, v232, v208
	v_mul_f32_e32 v209, v233, v209
	v_cvt_pk_bf16_f32 v228, v202, v203
	v_cvt_pk_bf16_f32 v229, v204, v205
	v_cvt_pk_bf16_f32 v230, v206, v207
	v_cvt_pk_bf16_f32 v231, v208, v209
	global_store_dwordx4 v[134:135], v[228:231], off offset:256
	s_branch .Lp2e_b1_done
